# streaming nt hint on the read-once input loads of the two gate phases (4 and 10)
# speedup vs baseline: 1.0224x; 1.0056x over previous
; DI void phase_gdn_gate(const Params& p) {
;     const int lane = threadIdx.x & 63, gw = blockIdx.x * 8 + (threadIdx.x >> 6), nw = gridDim.x * 8;
;     const bf16_t* oraw = (const bf16_t*)(p.ws + WS_ORAW); const bf16_t* P0 = (const bf16_t*)(p.ws + WS_P0); bf16_t* og = (bf16_t*)(p.ws + WS_OG);
;     for (int tok = gw; tok < T_TOK; tok += nw) {
;         const u32x4 a0 = *(const u32x4*)(oraw + (size_t)tok * 1024 + 16 * lane), a1 = *(const u32x4*)(oraw + (size_t)tok * 1024 + 16 * lane + 8);
;         const u32x4 z0 = *(const u32x4*)(P0 + (size_t)tok * LDP0 + 3072 + 16 * lane), z1 = *(const u32x4*)(P0 + (size_t)tok * LDP0 + 3072 + 16 * lane + 8);
.LBB0_930:
	s_cmp_lt_i32 s80, 5
	s_cselect_b64 s[4:5], -1, 0
	v_add_u32_e32 v162, s83, v155
	s_movk_i32 s3, 0x4400
	s_and_b64 s[0:1], s[4:5], s[0:1]
	v_cmp_gt_i32_e64 s[44:45], s3, v162
	s_lshl_b32 s46, s94, 3
	s_and_b64 s[0:1], s[44:45], s[0:1]
	v_ashrrev_i32_e32 v163, 31, v162
	v_mbcnt_lo_u32_b32 v197, -1, 0
	v_and_b32_e32 v196, 63, v1
	s_and_saveexec_b64 s[6:7], s[0:1]
	s_cbranch_execz .LBB0_933
	v_readlane_b32 s14, v238, 6
	v_readlane_b32 s15, v238, 7
	v_lshlrev_b32_e32 v2, 4, v196
	v_and_b32_e32 v3, 15, v196
	v_lshlrev_b32_e32 v3, 5, v3
	s_add_u32 s10, s78, 0x3c80000
	s_addc_u32 s11, s79, 0
	s_add_u32 s12, s78, 0x1d481800
	s_addc_u32 s13, s79, 0
	s_add_u32 s16, s78, 0x8080000
	s_addc_u32 s17, s79, 0
	v_readfirstlane_b32 s8, v162
	v_mov_b32_e32 v15, 0x358637bd
	s_cmpk_lt_u32 s8, 0x400
	s_cbranch_scc0 .Lg4_no9a
	s_mul_i32 s9, s46, 8
	s_add_i32 s9, s9, s8
	s_lshl_b32 s3, s9, 11
	s_add_u32 s20, s10, s3
	s_addc_u32 s21, s11, 0
	s_mul_i32 s3, s9, 0x2200
	s_add_u32 s22, s12, s3
	s_addc_u32 s23, s13, 0
	global_load_dwordx4 v[198:201], v2, s[20:21] nt
	global_load_dwordx4 v[202:205], v2, s[20:21] offset:1024 nt
	global_load_dwordx4 v[206:209], v2, s[22:23] nt
	global_load_dwordx4 v[210:213], v2, s[22:23] offset:1024 nt
.Lg4_no9a:
	global_load_dwordx4 v[16:19], v3, s[14:15] nt
	global_load_dwordx4 v[20:23], v3, s[14:15] offset:16 nt
	global_load_dwordx4 v[24:27], v3, s[14:15] nt
	global_load_dwordx4 v[28:31], v3, s[14:15] offset:16 nt
	s_mul_i32 s9, s46, 0
	s_add_i32 s9, s9, s8
	s_lshl_b32 s3, s9, 11
	s_add_u32 s20, s10, s3
	s_addc_u32 s21, s11, 0
	s_mul_i32 s3, s9, 0x2200
	s_add_u32 s22, s12, s3
	s_addc_u32 s23, s13, 0
	global_load_dwordx4 v[32:35], v2, s[20:21] nt
	global_load_dwordx4 v[36:39], v2, s[20:21] offset:1024 nt
	global_load_dwordx4 v[40:43], v2, s[22:23] nt
	global_load_dwordx4 v[44:47], v2, s[22:23] offset:1024 nt
	s_mul_i32 s9, s46, 1
	s_add_i32 s9, s9, s8
	s_lshl_b32 s3, s9, 11
	s_add_u32 s20, s10, s3
	s_addc_u32 s21, s11, 0
	s_mul_i32 s3, s9, 0x2200
	s_add_u32 s22, s12, s3
	s_addc_u32 s23, s13, 0
	global_load_dwordx4 v[48:51], v2, s[20:21] nt
	global_load_dwordx4 v[52:55], v2, s[20:21] offset:1024 nt
	global_load_dwordx4 v[56:59], v2, s[22:23] nt
	global_load_dwordx4 v[60:63], v2, s[22:23] offset:1024 nt
	s_mul_i32 s9, s46, 2
	s_add_i32 s9, s9, s8
	s_lshl_b32 s3, s9, 11
	s_add_u32 s20, s10, s3
	s_addc_u32 s21, s11, 0
	s_mul_i32 s3, s9, 0x2200
	s_add_u32 s22, s12, s3
	s_addc_u32 s23, s13, 0
	global_load_dwordx4 v[64:67], v2, s[20:21] nt
	global_load_dwordx4 v[68:71], v2, s[20:21] offset:1024 nt
	global_load_dwordx4 v[72:75], v2, s[22:23] nt
	global_load_dwordx4 v[76:79], v2, s[22:23] offset:1024 nt
	s_mul_i32 s9, s46, 3
	s_add_i32 s9, s9, s8
	s_lshl_b32 s3, s9, 11
	s_add_u32 s20, s10, s3
	s_addc_u32 s21, s11, 0
	s_mul_i32 s3, s9, 0x2200
	s_add_u32 s22, s12, s3
	s_addc_u32 s23, s13, 0
	global_load_dwordx4 v[80:83], v2, s[20:21] nt
	global_load_dwordx4 v[84:87], v2, s[20:21] offset:1024 nt
	global_load_dwordx4 v[88:91], v2, s[22:23] nt
	global_load_dwordx4 v[92:95], v2, s[22:23] offset:1024 nt
	s_mul_i32 s9, s46, 4
	s_add_i32 s9, s9, s8
	s_lshl_b32 s3, s9, 11
	s_add_u32 s20, s10, s3
	s_addc_u32 s21, s11, 0
	s_mul_i32 s3, s9, 0x2200
	s_add_u32 s22, s12, s3
	s_addc_u32 s23, s13, 0
	global_load_dwordx4 v[96:99], v2, s[20:21] nt
	global_load_dwordx4 v[100:103], v2, s[20:21] offset:1024 nt
	global_load_dwordx4 v[104:107], v2, s[22:23] nt
	global_load_dwordx4 v[108:111], v2, s[22:23] offset:1024 nt
	s_mul_i32 s9, s46, 5
	s_add_i32 s9, s9, s8
	s_lshl_b32 s3, s9, 11
	s_add_u32 s20, s10, s3
	s_addc_u32 s21, s11, 0
	s_mul_i32 s3, s9, 0x2200
	s_add_u32 s22, s12, s3
	s_addc_u32 s23, s13, 0
	global_load_dwordx4 v[112:115], v2, s[20:21] nt
	global_load_dwordx4 v[116:119], v2, s[20:21] offset:1024 nt
	global_load_dwordx4 v[120:123], v2, s[22:23] nt
	global_load_dwordx4 v[124:127], v2, s[22:23] offset:1024 nt
	s_mul_i32 s9, s46, 6
	s_add_i32 s9, s9, s8
	s_lshl_b32 s3, s9, 11
	s_add_u32 s20, s10, s3
	s_addc_u32 s21, s11, 0
	s_mul_i32 s3, s9, 0x2200
	s_add_u32 s22, s12, s3
	s_addc_u32 s23, s13, 0
	global_load_dwordx4 v[128:131], v2, s[20:21] nt
	global_load_dwordx4 v[132:135], v2, s[20:21] offset:1024 nt
	global_load_dwordx4 v[136:139], v2, s[22:23] nt
	global_load_dwordx4 v[140:143], v2, s[22:23] offset:1024 nt
	s_mul_i32 s9, s46, 7
	s_add_i32 s9, s9, s8
	s_lshl_b32 s3, s9, 11
	s_add_u32 s20, s10, s3
	s_addc_u32 s21, s11, 0
	s_mul_i32 s3, s9, 0x2200
	s_add_u32 s22, s12, s3
	s_addc_u32 s23, s13, 0
	global_load_dwordx4 v[168:171], v2, s[20:21] nt
	global_load_dwordx4 v[172:175], v2, s[20:21] offset:1024 nt
	global_load_dwordx4 v[176:179], v2, s[22:23] nt
	global_load_dwordx4 v[180:183], v2, s[22:23] offset:1024 nt
	s_waitcnt vmcnt(28)
; DI unsigned pk_bf16(float a, float b) { f32x2 v = {a, b}; bf2_t r = __builtin_convertvector(v, bf2_t); return __builtin_bit_cast(unsigned, r); }
; DI float bflo(unsigned u) { return __uint_as_float(u << 16); }
; DI float bfhi(unsigned u) { return __uint_as_float(u & 0xffff0000u); }
; DI float silu_f(float x) { return x * __builtin_amdgcn_rcpf(1.f + __expf(-x)); }
; DI void phase_gdn_gate(const Params& p) {
;     ...
;         const u32x4 z0 = *(const u32x4*)(P0 + (size_t)tok * LDP0 + 3072 + 16 * lane), z1 = *(const u32x4*)(P0 + (size_t)tok * LDP0 + 3072 + 16 * lane + 8);
;         float o[16], z[16];
;         const unsigned au[8] = {a0.x, a0.y, a0.z, a0.w, a1.x, a1.y, a1.z, a1.w}, zu[8] = {z0.x, z0.y, z0.z, z0.w, z1.x, z1.y, z1.z, z1.w};
;         float ss = 0.f;
; #pragma unroll
;         for (int i = 0; i < 8; ++i) { o[2 * i] = bflo(au[i]); o[2 * i + 1] = bfhi(au[i]); z[2 * i] = bflo(zu[i]); z[2 * i + 1] = bfhi(zu[i]); ss += o[2 * i] * o[2 * i] + o[2 * i + 1] * o[2 * i + 1]; }
;         ss += __shfl_xor(ss, 1); ss += __shfl_xor(ss, 2); ss += __shfl_xor(ss, 4);
;         const float rstd = rsqrtf(ss * (1.f / 128.f) + 1e-6f);
;         const int d0 = (16 * lane) & 127;
;         unsigned r[8];
; #pragma unroll
;         for (int i = 0; i < 8; ++i) { const float v0 = o[2 * i] * rstd * p.onorm_a[d0 + 2 * i] * silu_f(z[2 * i]), v1 = o[2 * i + 1] * rstd * p.onorm_a[d0 + 2 * i + 1] * silu_f(z[2 * i + 1]); r[i] = pk_bf16(v0, v1); }
;         *(u32x4*)(og + (size_t)tok * 1024 + 16 * lane) = (u32x4){r[0], r[1], r[2], r[3]};
;         *(u32x4*)(og + (size_t)tok * 1024 + 16 * lane + 8) = (u32x4){r[4], r[5], r[6], r[7]};
	v_lshlrev_b32_e32 v214, 16, v32
	v_and_b32_e32 v215, 0xffff0000, v32
	v_lshlrev_b32_e32 v216, 16, v33
	v_and_b32_e32 v217, 0xffff0000, v33
	v_lshlrev_b32_e32 v218, 16, v34
	v_and_b32_e32 v219, 0xffff0000, v34
	v_lshlrev_b32_e32 v220, 16, v35
	v_and_b32_e32 v221, 0xffff0000, v35
	v_lshlrev_b32_e32 v222, 16, v36
	v_and_b32_e32 v223, 0xffff0000, v36
	v_lshlrev_b32_e32 v224, 16, v37
	v_and_b32_e32 v225, 0xffff0000, v37
	v_lshlrev_b32_e32 v226, 16, v38
	v_and_b32_e32 v227, 0xffff0000, v38
	v_lshlrev_b32_e32 v228, 16, v39
	v_and_b32_e32 v229, 0xffff0000, v39
	v_mul_f32_e32 v144, v214, v214
	v_fmac_f32_e32 v144, v215, v215
	v_fmac_f32_e32 v144, v216, v216
	v_fmac_f32_e32 v144, v217, v217
	v_fmac_f32_e32 v144, v218, v218
	v_fmac_f32_e32 v144, v219, v219
	v_fmac_f32_e32 v144, v220, v220
	v_fmac_f32_e32 v144, v221, v221
	v_mul_f32_e32 v145, v222, v222
	v_fmac_f32_e32 v145, v223, v223
	v_fmac_f32_e32 v145, v224, v224
	v_fmac_f32_e32 v145, v225, v225
	v_fmac_f32_e32 v145, v226, v226
	v_fmac_f32_e32 v145, v227, v227
	v_fmac_f32_e32 v145, v228, v228
	v_fmac_f32_e32 v145, v229, v229
	v_lshlrev_b32_e32 v240, 16, v40
	v_and_b32_e32 v241, 0xffff0000, v40
	v_lshlrev_b32_e32 v242, 16, v41
	v_and_b32_e32 v243, 0xffff0000, v41
	v_lshlrev_b32_e32 v244, 16, v42
	v_and_b32_e32 v245, 0xffff0000, v42
	v_lshlrev_b32_e32 v246, 16, v43
	v_and_b32_e32 v247, 0xffff0000, v43
	v_lshlrev_b32_e32 v248, 16, v44
	v_and_b32_e32 v249, 0xffff0000, v44
	v_lshlrev_b32_e32 v250, 16, v45
	v_and_b32_e32 v251, 0xffff0000, v45
	v_lshlrev_b32_e32 v252, 16, v46
	v_and_b32_e32 v253, 0xffff0000, v46
	v_lshlrev_b32_e32 v254, 16, v47
	v_and_b32_e32 v255, 0xffff0000, v47
	s_nop 1
	v_add_f32_dpp v144, v144, v144 quad_perm:[1,0,3,2] row_mask:0xf bank_mask:0xf
	v_add_f32_dpp v145, v145, v145 quad_perm:[1,0,3,2] row_mask:0xf bank_mask:0xf
	s_nop 1
	v_add_f32_dpp v144, v144, v144 quad_perm:[2,3,0,1] row_mask:0xf bank_mask:0xf
	v_add_f32_dpp v145, v145, v145 quad_perm:[2,3,0,1] row_mask:0xf bank_mask:0xf
	s_nop 1
	v_add_f32_dpp v144, v144, v144 row_ror:4 row_mask:0xf bank_mask:0xf
	v_add_f32_dpp v145, v145, v145 row_ror:4 row_mask:0xf bank_mask:0xf
	s_nop 1
	v_add_f32_dpp v144, v144, v144 row_ror:8 row_mask:0xf bank_mask:0xf
	v_add_f32_dpp v145, v145, v145 row_ror:8 row_mask:0xf bank_mask:0xf
	v_fmamk_f32 v144, v144, 0x3c000000, v15
	v_fmamk_f32 v145, v145, 0x3c000000, v15
	v_rsq_f32_e32 v144, v144
	v_rsq_f32_e32 v145, v145
	v_mul_f32_e32 v148, 0xbfb8aa3b, v240
	v_mul_f32_e32 v149, 0xbfb8aa3b, v241
	v_mul_f32_e32 v150, 0xbfb8aa3b, v242
	v_mul_f32_e32 v151, 0xbfb8aa3b, v243
	v_mul_f32_e32 v4, 0xbfb8aa3b, v244
	v_mul_f32_e32 v5, 0xbfb8aa3b, v245
	v_mul_f32_e32 v6, 0xbfb8aa3b, v246
	v_mul_f32_e32 v7, 0xbfb8aa3b, v247
	v_exp_f32_e32 v148, v148
	v_exp_f32_e32 v149, v149
	v_exp_f32_e32 v150, v150
	v_exp_f32_e32 v151, v151
	v_exp_f32_e32 v4, v4
	v_exp_f32_e32 v5, v5
	v_exp_f32_e32 v6, v6
	v_exp_f32_e32 v7, v7
	v_add_f32_e32 v148, 1.0, v148
	v_add_f32_e32 v149, 1.0, v149
	v_add_f32_e32 v150, 1.0, v150
	v_add_f32_e32 v151, 1.0, v151
	v_add_f32_e32 v4, 1.0, v4
	v_add_f32_e32 v5, 1.0, v5
	v_add_f32_e32 v6, 1.0, v6
	v_add_f32_e32 v7, 1.0, v7
	v_rcp_f32_e32 v148, v148
	v_rcp_f32_e32 v149, v149
	v_rcp_f32_e32 v150, v150
	v_rcp_f32_e32 v151, v151
	v_rcp_f32_e32 v4, v4
	v_rcp_f32_e32 v5, v5
	v_rcp_f32_e32 v6, v6
	v_rcp_f32_e32 v7, v7
	v_mul_f32_e32 v240, v148, v240
	v_mul_f32_e32 v241, v149, v241
	v_mul_f32_e32 v242, v150, v242
	v_mul_f32_e32 v243, v151, v243
	v_mul_f32_e32 v244, v4, v244
	v_mul_f32_e32 v245, v5, v245
	v_mul_f32_e32 v246, v6, v246
	v_mul_f32_e32 v247, v7, v247
	v_mul_f32_e32 v148, 0xbfb8aa3b, v248
	v_mul_f32_e32 v149, 0xbfb8aa3b, v249
	v_mul_f32_e32 v150, 0xbfb8aa3b, v250
	v_mul_f32_e32 v151, 0xbfb8aa3b, v251
	v_mul_f32_e32 v4, 0xbfb8aa3b, v252
	v_mul_f32_e32 v5, 0xbfb8aa3b, v253
	v_mul_f32_e32 v6, 0xbfb8aa3b, v254
	v_mul_f32_e32 v7, 0xbfb8aa3b, v255
	v_exp_f32_e32 v148, v148
	v_exp_f32_e32 v149, v149
	v_exp_f32_e32 v150, v150
	v_exp_f32_e32 v151, v151
	v_exp_f32_e32 v4, v4
	v_exp_f32_e32 v5, v5
	v_exp_f32_e32 v6, v6
	v_exp_f32_e32 v7, v7
	v_add_f32_e32 v148, 1.0, v148
	v_add_f32_e32 v149, 1.0, v149
	v_add_f32_e32 v150, 1.0, v150
	v_add_f32_e32 v151, 1.0, v151
	v_add_f32_e32 v4, 1.0, v4
	v_add_f32_e32 v5, 1.0, v5
	v_add_f32_e32 v6, 1.0, v6
	v_add_f32_e32 v7, 1.0, v7
	v_rcp_f32_e32 v148, v148
	v_rcp_f32_e32 v149, v149
	v_rcp_f32_e32 v150, v150
	v_rcp_f32_e32 v151, v151
	v_rcp_f32_e32 v4, v4
	v_rcp_f32_e32 v5, v5
	v_rcp_f32_e32 v6, v6
	v_rcp_f32_e32 v7, v7
	v_mul_f32_e32 v248, v148, v248
	v_mul_f32_e32 v249, v149, v249
	v_mul_f32_e32 v250, v150, v250
	v_mul_f32_e32 v251, v151, v251
	v_mul_f32_e32 v252, v4, v252
	v_mul_f32_e32 v253, v5, v253
	v_mul_f32_e32 v254, v6, v254
	v_mul_f32_e32 v255, v7, v255
	v_mul_f32_e32 v214, v144, v214
	v_mul_f32_e32 v215, v144, v215
	v_mul_f32_e32 v216, v144, v216
	v_mul_f32_e32 v217, v144, v217
	v_mul_f32_e32 v218, v144, v218
	v_mul_f32_e32 v219, v144, v219
	v_mul_f32_e32 v220, v144, v220
	v_mul_f32_e32 v221, v144, v221
	v_mul_f32_e32 v222, v145, v222
	v_mul_f32_e32 v223, v145, v223
	v_mul_f32_e32 v224, v145, v224
	v_mul_f32_e32 v225, v145, v225
	v_mul_f32_e32 v226, v145, v226
	v_mul_f32_e32 v227, v145, v227
	v_mul_f32_e32 v228, v145, v228
	v_mul_f32_e32 v229, v145, v229
	v_mul_f32_e32 v214, v16, v214
	v_mul_f32_e32 v215, v17, v215
	v_mul_f32_e32 v216, v18, v216
	v_mul_f32_e32 v217, v19, v217
	v_mul_f32_e32 v218, v20, v218
	v_mul_f32_e32 v219, v21, v219
	v_mul_f32_e32 v220, v22, v220
	v_mul_f32_e32 v221, v23, v221
	v_mul_f32_e32 v222, v24, v222
	v_mul_f32_e32 v223, v25, v223
	v_mul_f32_e32 v224, v26, v224
	v_mul_f32_e32 v225, v27, v225
	v_mul_f32_e32 v226, v28, v226
	v_mul_f32_e32 v227, v29, v227
	v_mul_f32_e32 v228, v30, v228
	v_mul_f32_e32 v229, v31, v229
	v_mul_f32_e32 v214, v240, v214
	v_mul_f32_e32 v215, v241, v215
	v_mul_f32_e32 v216, v242, v216
	v_mul_f32_e32 v217, v243, v217
	v_mul_f32_e32 v218, v244, v218
	v_mul_f32_e32 v219, v245, v219
	v_mul_f32_e32 v220, v246, v220
	v_mul_f32_e32 v221, v247, v221
	v_mul_f32_e32 v222, v248, v222
	v_mul_f32_e32 v223, v249, v223
	v_mul_f32_e32 v224, v250, v224
	v_mul_f32_e32 v225, v251, v225
	v_mul_f32_e32 v226, v252, v226
	v_mul_f32_e32 v227, v253, v227
	v_mul_f32_e32 v228, v254, v228
	v_mul_f32_e32 v229, v255, v229
	v_cvt_pk_bf16_f32 v144, v214, v215
	v_cvt_pk_bf16_f32 v145, v216, v217
	v_cvt_pk_bf16_f32 v146, v218, v219
	v_cvt_pk_bf16_f32 v147, v220, v221
	v_cvt_pk_bf16_f32 v148, v222, v223
	v_cvt_pk_bf16_f32 v149, v224, v225
	v_cvt_pk_bf16_f32 v150, v226, v227
	v_cvt_pk_bf16_f32 v151, v228, v229
	s_mul_i32 s9, s46, 0
	s_add_i32 s9, s9, s8
	s_lshl_b32 s3, s9, 11
	s_add_u32 s24, s16, s3
	s_addc_u32 s25, s17, 0
	global_store_dwordx4 v2, v[144:147], s[24:25]
	global_store_dwordx4 v2, v[148:151], s[24:25] offset:1024
	s_waitcnt vmcnt(26)
; DI unsigned pk_bf16(float a, float b) { f32x2 v = {a, b}; bf2_t r = __builtin_convertvector(v, bf2_t); return __builtin_bit_cast(unsigned, r); }
; DI float bflo(unsigned u) { return __uint_as_float(u << 16); }
; DI float bfhi(unsigned u) { return __uint_as_float(u & 0xffff0000u); }
; DI float silu_f(float x) { return x * __builtin_amdgcn_rcpf(1.f + __expf(-x)); }
; DI void phase_gdn_gate(const Params& p) {
;     ...
;         const u32x4 z0 = *(const u32x4*)(P0 + (size_t)tok * LDP0 + 3072 + 16 * lane), z1 = *(const u32x4*)(P0 + (size_t)tok * LDP0 + 3072 + 16 * lane + 8);
;         float o[16], z[16];
;         const unsigned au[8] = {a0.x, a0.y, a0.z, a0.w, a1.x, a1.y, a1.z, a1.w}, zu[8] = {z0.x, z0.y, z0.z, z0.w, z1.x, z1.y, z1.z, z1.w};
;         float ss = 0.f;
; #pragma unroll
;         for (int i = 0; i < 8; ++i) { o[2 * i] = bflo(au[i]); o[2 * i + 1] = bfhi(au[i]); z[2 * i] = bflo(zu[i]); z[2 * i + 1] = bfhi(zu[i]); ss += o[2 * i] * o[2 * i] + o[2 * i + 1] * o[2 * i + 1]; }
;         ss += __shfl_xor(ss, 1); ss += __shfl_xor(ss, 2); ss += __shfl_xor(ss, 4);
;         const float rstd = rsqrtf(ss * (1.f / 128.f) + 1e-6f);
;         const int d0 = (16 * lane) & 127;
;         unsigned r[8];
; #pragma unroll
;         for (int i = 0; i < 8; ++i) { const float v0 = o[2 * i] * rstd * p.onorm_a[d0 + 2 * i] * silu_f(z[2 * i]), v1 = o[2 * i + 1] * rstd * p.onorm_a[d0 + 2 * i + 1] * silu_f(z[2 * i + 1]); r[i] = pk_bf16(v0, v1); }
;         *(u32x4*)(og + (size_t)tok * 1024 + 16 * lane) = (u32x4){r[0], r[1], r[2], r[3]};
;         *(u32x4*)(og + (size_t)tok * 1024 + 16 * lane + 8) = (u32x4){r[4], r[5], r[6], r[7]};
	v_lshlrev_b32_e32 v214, 16, v48
	v_and_b32_e32 v215, 0xffff0000, v48
	v_lshlrev_b32_e32 v216, 16, v49
	v_and_b32_e32 v217, 0xffff0000, v49
	v_lshlrev_b32_e32 v218, 16, v50
	v_and_b32_e32 v219, 0xffff0000, v50
	v_lshlrev_b32_e32 v220, 16, v51
	v_and_b32_e32 v221, 0xffff0000, v51
	v_lshlrev_b32_e32 v222, 16, v52
	v_and_b32_e32 v223, 0xffff0000, v52
	v_lshlrev_b32_e32 v224, 16, v53
	v_and_b32_e32 v225, 0xffff0000, v53
	v_lshlrev_b32_e32 v226, 16, v54
	v_and_b32_e32 v227, 0xffff0000, v54
	v_lshlrev_b32_e32 v228, 16, v55
	v_and_b32_e32 v229, 0xffff0000, v55
	v_mul_f32_e32 v144, v214, v214
	v_fmac_f32_e32 v144, v215, v215
	v_fmac_f32_e32 v144, v216, v216
	v_fmac_f32_e32 v144, v217, v217
	v_fmac_f32_e32 v144, v218, v218
	v_fmac_f32_e32 v144, v219, v219
	v_fmac_f32_e32 v144, v220, v220
	v_fmac_f32_e32 v144, v221, v221
	v_mul_f32_e32 v145, v222, v222
	v_fmac_f32_e32 v145, v223, v223
	v_fmac_f32_e32 v145, v224, v224
	v_fmac_f32_e32 v145, v225, v225
	v_fmac_f32_e32 v145, v226, v226
	v_fmac_f32_e32 v145, v227, v227
	v_fmac_f32_e32 v145, v228, v228
	v_fmac_f32_e32 v145, v229, v229
	v_lshlrev_b32_e32 v240, 16, v56
	v_and_b32_e32 v241, 0xffff0000, v56
	v_lshlrev_b32_e32 v242, 16, v57
	v_and_b32_e32 v243, 0xffff0000, v57
	v_lshlrev_b32_e32 v244, 16, v58
	v_and_b32_e32 v245, 0xffff0000, v58
	v_lshlrev_b32_e32 v246, 16, v59
	v_and_b32_e32 v247, 0xffff0000, v59
	v_lshlrev_b32_e32 v248, 16, v60
	v_and_b32_e32 v249, 0xffff0000, v60
	v_lshlrev_b32_e32 v250, 16, v61
	v_and_b32_e32 v251, 0xffff0000, v61
	v_lshlrev_b32_e32 v252, 16, v62
	v_and_b32_e32 v253, 0xffff0000, v62
	v_lshlrev_b32_e32 v254, 16, v63
	v_and_b32_e32 v255, 0xffff0000, v63
	s_nop 1
	v_add_f32_dpp v144, v144, v144 quad_perm:[1,0,3,2] row_mask:0xf bank_mask:0xf
	v_add_f32_dpp v145, v145, v145 quad_perm:[1,0,3,2] row_mask:0xf bank_mask:0xf
	s_nop 1
	v_add_f32_dpp v144, v144, v144 quad_perm:[2,3,0,1] row_mask:0xf bank_mask:0xf
	v_add_f32_dpp v145, v145, v145 quad_perm:[2,3,0,1] row_mask:0xf bank_mask:0xf
	s_nop 1
	v_add_f32_dpp v144, v144, v144 row_ror:4 row_mask:0xf bank_mask:0xf
	v_add_f32_dpp v145, v145, v145 row_ror:4 row_mask:0xf bank_mask:0xf
	s_nop 1
	v_add_f32_dpp v144, v144, v144 row_ror:8 row_mask:0xf bank_mask:0xf
	v_add_f32_dpp v145, v145, v145 row_ror:8 row_mask:0xf bank_mask:0xf
	v_fmamk_f32 v144, v144, 0x3c000000, v15
	v_fmamk_f32 v145, v145, 0x3c000000, v15
	v_rsq_f32_e32 v144, v144
	v_rsq_f32_e32 v145, v145
	v_mul_f32_e32 v148, 0xbfb8aa3b, v240
	v_mul_f32_e32 v149, 0xbfb8aa3b, v241
	v_mul_f32_e32 v150, 0xbfb8aa3b, v242
	v_mul_f32_e32 v151, 0xbfb8aa3b, v243
	v_mul_f32_e32 v4, 0xbfb8aa3b, v244
	v_mul_f32_e32 v5, 0xbfb8aa3b, v245
	v_mul_f32_e32 v6, 0xbfb8aa3b, v246
	v_mul_f32_e32 v7, 0xbfb8aa3b, v247
	v_exp_f32_e32 v148, v148
	v_exp_f32_e32 v149, v149
	v_exp_f32_e32 v150, v150
	v_exp_f32_e32 v151, v151
	v_exp_f32_e32 v4, v4
	v_exp_f32_e32 v5, v5
	v_exp_f32_e32 v6, v6
	v_exp_f32_e32 v7, v7
	v_add_f32_e32 v148, 1.0, v148
	v_add_f32_e32 v149, 1.0, v149
	v_add_f32_e32 v150, 1.0, v150
	v_add_f32_e32 v151, 1.0, v151
	v_add_f32_e32 v4, 1.0, v4
	v_add_f32_e32 v5, 1.0, v5
	v_add_f32_e32 v6, 1.0, v6
	v_add_f32_e32 v7, 1.0, v7
	v_rcp_f32_e32 v148, v148
	v_rcp_f32_e32 v149, v149
	v_rcp_f32_e32 v150, v150
	v_rcp_f32_e32 v151, v151
	v_rcp_f32_e32 v4, v4
	v_rcp_f32_e32 v5, v5
	v_rcp_f32_e32 v6, v6
	v_rcp_f32_e32 v7, v7
	v_mul_f32_e32 v240, v148, v240
	v_mul_f32_e32 v241, v149, v241
	v_mul_f32_e32 v242, v150, v242
	v_mul_f32_e32 v243, v151, v243
	v_mul_f32_e32 v244, v4, v244
	v_mul_f32_e32 v245, v5, v245
	v_mul_f32_e32 v246, v6, v246
	v_mul_f32_e32 v247, v7, v247
	v_mul_f32_e32 v148, 0xbfb8aa3b, v248
	v_mul_f32_e32 v149, 0xbfb8aa3b, v249
	v_mul_f32_e32 v150, 0xbfb8aa3b, v250
	v_mul_f32_e32 v151, 0xbfb8aa3b, v251
	v_mul_f32_e32 v4, 0xbfb8aa3b, v252
	v_mul_f32_e32 v5, 0xbfb8aa3b, v253
	v_mul_f32_e32 v6, 0xbfb8aa3b, v254
	v_mul_f32_e32 v7, 0xbfb8aa3b, v255
	v_exp_f32_e32 v148, v148
	v_exp_f32_e32 v149, v149
	v_exp_f32_e32 v150, v150
	v_exp_f32_e32 v151, v151
	v_exp_f32_e32 v4, v4
	v_exp_f32_e32 v5, v5
	v_exp_f32_e32 v6, v6
	v_exp_f32_e32 v7, v7
	v_add_f32_e32 v148, 1.0, v148
	v_add_f32_e32 v149, 1.0, v149
	v_add_f32_e32 v150, 1.0, v150
	v_add_f32_e32 v151, 1.0, v151
	v_add_f32_e32 v4, 1.0, v4
	v_add_f32_e32 v5, 1.0, v5
	v_add_f32_e32 v6, 1.0, v6
	v_add_f32_e32 v7, 1.0, v7
	v_rcp_f32_e32 v148, v148
	v_rcp_f32_e32 v149, v149
	v_rcp_f32_e32 v150, v150
	v_rcp_f32_e32 v151, v151
	v_rcp_f32_e32 v4, v4
	v_rcp_f32_e32 v5, v5
	v_rcp_f32_e32 v6, v6
	v_rcp_f32_e32 v7, v7
	v_mul_f32_e32 v248, v148, v248
	v_mul_f32_e32 v249, v149, v249
	v_mul_f32_e32 v250, v150, v250
	v_mul_f32_e32 v251, v151, v251
	v_mul_f32_e32 v252, v4, v252
	v_mul_f32_e32 v253, v5, v253
	v_mul_f32_e32 v254, v6, v254
	v_mul_f32_e32 v255, v7, v255
	v_mul_f32_e32 v214, v144, v214
	v_mul_f32_e32 v215, v144, v215
	v_mul_f32_e32 v216, v144, v216
	v_mul_f32_e32 v217, v144, v217
	v_mul_f32_e32 v218, v144, v218
	v_mul_f32_e32 v219, v144, v219
	v_mul_f32_e32 v220, v144, v220
	v_mul_f32_e32 v221, v144, v221
	v_mul_f32_e32 v222, v145, v222
	v_mul_f32_e32 v223, v145, v223
	v_mul_f32_e32 v224, v145, v224
	v_mul_f32_e32 v225, v145, v225
	v_mul_f32_e32 v226, v145, v226
	v_mul_f32_e32 v227, v145, v227
	v_mul_f32_e32 v228, v145, v228
	v_mul_f32_e32 v229, v145, v229
	v_mul_f32_e32 v214, v16, v214
	v_mul_f32_e32 v215, v17, v215
	v_mul_f32_e32 v216, v18, v216
	v_mul_f32_e32 v217, v19, v217
	v_mul_f32_e32 v218, v20, v218
	v_mul_f32_e32 v219, v21, v219
	v_mul_f32_e32 v220, v22, v220
	v_mul_f32_e32 v221, v23, v221
	v_mul_f32_e32 v222, v24, v222
	v_mul_f32_e32 v223, v25, v223
	v_mul_f32_e32 v224, v26, v224
	v_mul_f32_e32 v225, v27, v225
	v_mul_f32_e32 v226, v28, v226
	v_mul_f32_e32 v227, v29, v227
	v_mul_f32_e32 v228, v30, v228
	v_mul_f32_e32 v229, v31, v229
	v_mul_f32_e32 v214, v240, v214
	v_mul_f32_e32 v215, v241, v215
	v_mul_f32_e32 v216, v242, v216
	v_mul_f32_e32 v217, v243, v217
	v_mul_f32_e32 v218, v244, v218
	v_mul_f32_e32 v219, v245, v219
	v_mul_f32_e32 v220, v246, v220
	v_mul_f32_e32 v221, v247, v221
	v_mul_f32_e32 v222, v248, v222
	v_mul_f32_e32 v223, v249, v223
	v_mul_f32_e32 v224, v250, v224
	v_mul_f32_e32 v225, v251, v225
	v_mul_f32_e32 v226, v252, v226
	v_mul_f32_e32 v227, v253, v227
	v_mul_f32_e32 v228, v254, v228
	v_mul_f32_e32 v229, v255, v229
	v_cvt_pk_bf16_f32 v144, v214, v215
	v_cvt_pk_bf16_f32 v145, v216, v217
	v_cvt_pk_bf16_f32 v146, v218, v219
	v_cvt_pk_bf16_f32 v147, v220, v221
	v_cvt_pk_bf16_f32 v148, v222, v223
	v_cvt_pk_bf16_f32 v149, v224, v225
	v_cvt_pk_bf16_f32 v150, v226, v227
	v_cvt_pk_bf16_f32 v151, v228, v229
	s_mul_i32 s9, s46, 1
	s_add_i32 s9, s9, s8
	s_lshl_b32 s3, s9, 11
	s_add_u32 s24, s16, s3
	s_addc_u32 s25, s17, 0
	global_store_dwordx4 v2, v[144:147], s[24:25]
	global_store_dwordx4 v2, v[148:151], s[24:25] offset:1024
	s_waitcnt vmcnt(24)
; DI unsigned pk_bf16(float a, float b) { f32x2 v = {a, b}; bf2_t r = __builtin_convertvector(v, bf2_t); return __builtin_bit_cast(unsigned, r); }
; DI float bflo(unsigned u) { return __uint_as_float(u << 16); }
; DI float bfhi(unsigned u) { return __uint_as_float(u & 0xffff0000u); }
; DI float silu_f(float x) { return x * __builtin_amdgcn_rcpf(1.f + __expf(-x)); }
; DI void phase_gdn_gate(const Params& p) {
;     ...
;         const u32x4 z0 = *(const u32x4*)(P0 + (size_t)tok * LDP0 + 3072 + 16 * lane), z1 = *(const u32x4*)(P0 + (size_t)tok * LDP0 + 3072 + 16 * lane + 8);
;         float o[16], z[16];
;         const unsigned au[8] = {a0.x, a0.y, a0.z, a0.w, a1.x, a1.y, a1.z, a1.w}, zu[8] = {z0.x, z0.y, z0.z, z0.w, z1.x, z1.y, z1.z, z1.w};
;         float ss = 0.f;
; #pragma unroll
;         for (int i = 0; i < 8; ++i) { o[2 * i] = bflo(au[i]); o[2 * i + 1] = bfhi(au[i]); z[2 * i] = bflo(zu[i]); z[2 * i + 1] = bfhi(zu[i]); ss += o[2 * i] * o[2 * i] + o[2 * i + 1] * o[2 * i + 1]; }
;         ss += __shfl_xor(ss, 1); ss += __shfl_xor(ss, 2); ss += __shfl_xor(ss, 4);
;         const float rstd = rsqrtf(ss * (1.f / 128.f) + 1e-6f);
;         const int d0 = (16 * lane) & 127;
;         unsigned r[8];
; #pragma unroll
;         for (int i = 0; i < 8; ++i) { const float v0 = o[2 * i] * rstd * p.onorm_a[d0 + 2 * i] * silu_f(z[2 * i]), v1 = o[2 * i + 1] * rstd * p.onorm_a[d0 + 2 * i + 1] * silu_f(z[2 * i + 1]); r[i] = pk_bf16(v0, v1); }
;         *(u32x4*)(og + (size_t)tok * 1024 + 16 * lane) = (u32x4){r[0], r[1], r[2], r[3]};
;         *(u32x4*)(og + (size_t)tok * 1024 + 16 * lane + 8) = (u32x4){r[4], r[5], r[6], r[7]};
	v_lshlrev_b32_e32 v214, 16, v64
	v_and_b32_e32 v215, 0xffff0000, v64
	v_lshlrev_b32_e32 v216, 16, v65
	v_and_b32_e32 v217, 0xffff0000, v65
	v_lshlrev_b32_e32 v218, 16, v66
	v_and_b32_e32 v219, 0xffff0000, v66
	v_lshlrev_b32_e32 v220, 16, v67
	v_and_b32_e32 v221, 0xffff0000, v67
	v_lshlrev_b32_e32 v222, 16, v68
	v_and_b32_e32 v223, 0xffff0000, v68
	v_lshlrev_b32_e32 v224, 16, v69
	v_and_b32_e32 v225, 0xffff0000, v69
	v_lshlrev_b32_e32 v226, 16, v70
	v_and_b32_e32 v227, 0xffff0000, v70
	v_lshlrev_b32_e32 v228, 16, v71
	v_and_b32_e32 v229, 0xffff0000, v71
	v_mul_f32_e32 v144, v214, v214
	v_fmac_f32_e32 v144, v215, v215
	v_fmac_f32_e32 v144, v216, v216
	v_fmac_f32_e32 v144, v217, v217
	v_fmac_f32_e32 v144, v218, v218
	v_fmac_f32_e32 v144, v219, v219
	v_fmac_f32_e32 v144, v220, v220
	v_fmac_f32_e32 v144, v221, v221
	v_mul_f32_e32 v145, v222, v222
	v_fmac_f32_e32 v145, v223, v223
	v_fmac_f32_e32 v145, v224, v224
	v_fmac_f32_e32 v145, v225, v225
	v_fmac_f32_e32 v145, v226, v226
	v_fmac_f32_e32 v145, v227, v227
	v_fmac_f32_e32 v145, v228, v228
	v_fmac_f32_e32 v145, v229, v229
	v_lshlrev_b32_e32 v240, 16, v72
	v_and_b32_e32 v241, 0xffff0000, v72
	v_lshlrev_b32_e32 v242, 16, v73
	v_and_b32_e32 v243, 0xffff0000, v73
	v_lshlrev_b32_e32 v244, 16, v74
	v_and_b32_e32 v245, 0xffff0000, v74
	v_lshlrev_b32_e32 v246, 16, v75
	v_and_b32_e32 v247, 0xffff0000, v75
	v_lshlrev_b32_e32 v248, 16, v76
	v_and_b32_e32 v249, 0xffff0000, v76
	v_lshlrev_b32_e32 v250, 16, v77
	v_and_b32_e32 v251, 0xffff0000, v77
	v_lshlrev_b32_e32 v252, 16, v78
	v_and_b32_e32 v253, 0xffff0000, v78
	v_lshlrev_b32_e32 v254, 16, v79
	v_and_b32_e32 v255, 0xffff0000, v79
	s_nop 1
	v_add_f32_dpp v144, v144, v144 quad_perm:[1,0,3,2] row_mask:0xf bank_mask:0xf
	v_add_f32_dpp v145, v145, v145 quad_perm:[1,0,3,2] row_mask:0xf bank_mask:0xf
	s_nop 1
	v_add_f32_dpp v144, v144, v144 quad_perm:[2,3,0,1] row_mask:0xf bank_mask:0xf
	v_add_f32_dpp v145, v145, v145 quad_perm:[2,3,0,1] row_mask:0xf bank_mask:0xf
	s_nop 1
	v_add_f32_dpp v144, v144, v144 row_ror:4 row_mask:0xf bank_mask:0xf
	v_add_f32_dpp v145, v145, v145 row_ror:4 row_mask:0xf bank_mask:0xf
	s_nop 1
	v_add_f32_dpp v144, v144, v144 row_ror:8 row_mask:0xf bank_mask:0xf
	v_add_f32_dpp v145, v145, v145 row_ror:8 row_mask:0xf bank_mask:0xf
	v_fmamk_f32 v144, v144, 0x3c000000, v15
	v_fmamk_f32 v145, v145, 0x3c000000, v15
	v_rsq_f32_e32 v144, v144
	v_rsq_f32_e32 v145, v145
	v_mul_f32_e32 v148, 0xbfb8aa3b, v240
	v_mul_f32_e32 v149, 0xbfb8aa3b, v241
	v_mul_f32_e32 v150, 0xbfb8aa3b, v242
	v_mul_f32_e32 v151, 0xbfb8aa3b, v243
	v_mul_f32_e32 v4, 0xbfb8aa3b, v244
	v_mul_f32_e32 v5, 0xbfb8aa3b, v245
	v_mul_f32_e32 v6, 0xbfb8aa3b, v246
	v_mul_f32_e32 v7, 0xbfb8aa3b, v247
	v_exp_f32_e32 v148, v148
	v_exp_f32_e32 v149, v149
	v_exp_f32_e32 v150, v150
	v_exp_f32_e32 v151, v151
	v_exp_f32_e32 v4, v4
	v_exp_f32_e32 v5, v5
	v_exp_f32_e32 v6, v6
	v_exp_f32_e32 v7, v7
	v_add_f32_e32 v148, 1.0, v148
	v_add_f32_e32 v149, 1.0, v149
	v_add_f32_e32 v150, 1.0, v150
	v_add_f32_e32 v151, 1.0, v151
	v_add_f32_e32 v4, 1.0, v4
	v_add_f32_e32 v5, 1.0, v5
	v_add_f32_e32 v6, 1.0, v6
	v_add_f32_e32 v7, 1.0, v7
	v_rcp_f32_e32 v148, v148
	v_rcp_f32_e32 v149, v149
	v_rcp_f32_e32 v150, v150
	v_rcp_f32_e32 v151, v151
	v_rcp_f32_e32 v4, v4
	v_rcp_f32_e32 v5, v5
	v_rcp_f32_e32 v6, v6
	v_rcp_f32_e32 v7, v7
	v_mul_f32_e32 v240, v148, v240
	v_mul_f32_e32 v241, v149, v241
	v_mul_f32_e32 v242, v150, v242
	v_mul_f32_e32 v243, v151, v243
	v_mul_f32_e32 v244, v4, v244
	v_mul_f32_e32 v245, v5, v245
	v_mul_f32_e32 v246, v6, v246
	v_mul_f32_e32 v247, v7, v247
	v_mul_f32_e32 v148, 0xbfb8aa3b, v248
	v_mul_f32_e32 v149, 0xbfb8aa3b, v249
	v_mul_f32_e32 v150, 0xbfb8aa3b, v250
	v_mul_f32_e32 v151, 0xbfb8aa3b, v251
	v_mul_f32_e32 v4, 0xbfb8aa3b, v252
	v_mul_f32_e32 v5, 0xbfb8aa3b, v253
	v_mul_f32_e32 v6, 0xbfb8aa3b, v254
	v_mul_f32_e32 v7, 0xbfb8aa3b, v255
	v_exp_f32_e32 v148, v148
	v_exp_f32_e32 v149, v149
	v_exp_f32_e32 v150, v150
	v_exp_f32_e32 v151, v151
	v_exp_f32_e32 v4, v4
	v_exp_f32_e32 v5, v5
	v_exp_f32_e32 v6, v6
	v_exp_f32_e32 v7, v7
	v_add_f32_e32 v148, 1.0, v148
	v_add_f32_e32 v149, 1.0, v149
	v_add_f32_e32 v150, 1.0, v150
	v_add_f32_e32 v151, 1.0, v151
	v_add_f32_e32 v4, 1.0, v4
	v_add_f32_e32 v5, 1.0, v5
	v_add_f32_e32 v6, 1.0, v6
	v_add_f32_e32 v7, 1.0, v7
	v_rcp_f32_e32 v148, v148
	v_rcp_f32_e32 v149, v149
	v_rcp_f32_e32 v150, v150
	v_rcp_f32_e32 v151, v151
	v_rcp_f32_e32 v4, v4
	v_rcp_f32_e32 v5, v5
	v_rcp_f32_e32 v6, v6
	v_rcp_f32_e32 v7, v7
	v_mul_f32_e32 v248, v148, v248
	v_mul_f32_e32 v249, v149, v249
	v_mul_f32_e32 v250, v150, v250
	v_mul_f32_e32 v251, v151, v251
	v_mul_f32_e32 v252, v4, v252
	v_mul_f32_e32 v253, v5, v253
	v_mul_f32_e32 v254, v6, v254
	v_mul_f32_e32 v255, v7, v255
	v_mul_f32_e32 v214, v144, v214
	v_mul_f32_e32 v215, v144, v215
	v_mul_f32_e32 v216, v144, v216
	v_mul_f32_e32 v217, v144, v217
	v_mul_f32_e32 v218, v144, v218
	v_mul_f32_e32 v219, v144, v219
	v_mul_f32_e32 v220, v144, v220
	v_mul_f32_e32 v221, v144, v221
	v_mul_f32_e32 v222, v145, v222
	v_mul_f32_e32 v223, v145, v223
	v_mul_f32_e32 v224, v145, v224
	v_mul_f32_e32 v225, v145, v225
	v_mul_f32_e32 v226, v145, v226
	v_mul_f32_e32 v227, v145, v227
	v_mul_f32_e32 v228, v145, v228
	v_mul_f32_e32 v229, v145, v229
	v_mul_f32_e32 v214, v16, v214
	v_mul_f32_e32 v215, v17, v215
	v_mul_f32_e32 v216, v18, v216
	v_mul_f32_e32 v217, v19, v217
	v_mul_f32_e32 v218, v20, v218
	v_mul_f32_e32 v219, v21, v219
	v_mul_f32_e32 v220, v22, v220
	v_mul_f32_e32 v221, v23, v221
	v_mul_f32_e32 v222, v24, v222
	v_mul_f32_e32 v223, v25, v223
	v_mul_f32_e32 v224, v26, v224
	v_mul_f32_e32 v225, v27, v225
	v_mul_f32_e32 v226, v28, v226
	v_mul_f32_e32 v227, v29, v227
	v_mul_f32_e32 v228, v30, v228
	v_mul_f32_e32 v229, v31, v229
	v_mul_f32_e32 v214, v240, v214
	v_mul_f32_e32 v215, v241, v215
	v_mul_f32_e32 v216, v242, v216
	v_mul_f32_e32 v217, v243, v217
	v_mul_f32_e32 v218, v244, v218
	v_mul_f32_e32 v219, v245, v219
	v_mul_f32_e32 v220, v246, v220
	v_mul_f32_e32 v221, v247, v221
	v_mul_f32_e32 v222, v248, v222
	v_mul_f32_e32 v223, v249, v223
	v_mul_f32_e32 v224, v250, v224
	v_mul_f32_e32 v225, v251, v225
	v_mul_f32_e32 v226, v252, v226
	v_mul_f32_e32 v227, v253, v227
	v_mul_f32_e32 v228, v254, v228
	v_mul_f32_e32 v229, v255, v229
	v_cvt_pk_bf16_f32 v144, v214, v215
	v_cvt_pk_bf16_f32 v145, v216, v217
	v_cvt_pk_bf16_f32 v146, v218, v219
	v_cvt_pk_bf16_f32 v147, v220, v221
	v_cvt_pk_bf16_f32 v148, v222, v223
	v_cvt_pk_bf16_f32 v149, v224, v225
	v_cvt_pk_bf16_f32 v150, v226, v227
	v_cvt_pk_bf16_f32 v151, v228, v229
	s_mul_i32 s9, s46, 2
	s_add_i32 s9, s9, s8
	s_lshl_b32 s3, s9, 11
	s_add_u32 s24, s16, s3
	s_addc_u32 s25, s17, 0
	global_store_dwordx4 v2, v[144:147], s[24:25]
	global_store_dwordx4 v2, v[148:151], s[24:25] offset:1024
	s_waitcnt vmcnt(22)
; DI unsigned pk_bf16(float a, float b) { f32x2 v = {a, b}; bf2_t r = __builtin_convertvector(v, bf2_t); return __builtin_bit_cast(unsigned, r); }
; DI float bflo(unsigned u) { return __uint_as_float(u << 16); }
; DI float bfhi(unsigned u) { return __uint_as_float(u & 0xffff0000u); }
; DI float silu_f(float x) { return x * __builtin_amdgcn_rcpf(1.f + __expf(-x)); }
; DI void phase_gdn_gate(const Params& p) {
;     ...
;     for (int tok = gw; tok < T_TOK; tok += nw) {
;         const u32x4 a0 = *(const u32x4*)(oraw + (size_t)tok * 1024 + 16 * lane), a1 = *(const u32x4*)(oraw + (size_t)tok * 1024 + 16 * lane + 8);
;         const u32x4 z0 = *(const u32x4*)(P0 + (size_t)tok * LDP0 + 3072 + 16 * lane), z1 = *(const u32x4*)(P0 + (size_t)tok * LDP0 + 3072 + 16 * lane + 8);
;         float o[16], z[16];
;         const unsigned au[8] = {a0.x, a0.y, a0.z, a0.w, a1.x, a1.y, a1.z, a1.w}, zu[8] = {z0.x, z0.y, z0.z, z0.w, z1.x, z1.y, z1.z, z1.w};
;         float ss = 0.f;
; #pragma unroll
;         for (int i = 0; i < 8; ++i) { o[2 * i] = bflo(au[i]); o[2 * i + 1] = bfhi(au[i]); z[2 * i] = bflo(zu[i]); z[2 * i + 1] = bfhi(zu[i]); ss += o[2 * i] * o[2 * i] + o[2 * i + 1] * o[2 * i + 1]; }
;         ss += __shfl_xor(ss, 1); ss += __shfl_xor(ss, 2); ss += __shfl_xor(ss, 4);
;         const float rstd = rsqrtf(ss * (1.f / 128.f) + 1e-6f);
;         const int d0 = (16 * lane) & 127;
;         unsigned r[8];
; #pragma unroll
;         for (int i = 0; i < 8; ++i) { const float v0 = o[2 * i] * rstd * p.onorm_a[d0 + 2 * i] * silu_f(z[2 * i]), v1 = o[2 * i + 1] * rstd * p.onorm_a[d0 + 2 * i + 1] * silu_f(z[2 * i + 1]); r[i] = pk_bf16(v0, v1); }
;         *(u32x4*)(og + (size_t)tok * 1024 + 16 * lane) = (u32x4){r[0], r[1], r[2], r[3]};
;         *(u32x4*)(og + (size_t)tok * 1024 + 16 * lane + 8) = (u32x4){r[4], r[5], r[6], r[7]};
	v_lshlrev_b32_e32 v214, 16, v80
	v_and_b32_e32 v215, 0xffff0000, v80
	v_lshlrev_b32_e32 v216, 16, v81
	v_and_b32_e32 v217, 0xffff0000, v81
	v_lshlrev_b32_e32 v218, 16, v82
	v_and_b32_e32 v219, 0xffff0000, v82
	v_lshlrev_b32_e32 v220, 16, v83
	v_and_b32_e32 v221, 0xffff0000, v83
	v_lshlrev_b32_e32 v222, 16, v84
	v_and_b32_e32 v223, 0xffff0000, v84
	v_lshlrev_b32_e32 v224, 16, v85
	v_and_b32_e32 v225, 0xffff0000, v85
	v_lshlrev_b32_e32 v226, 16, v86
	v_and_b32_e32 v227, 0xffff0000, v86
	v_lshlrev_b32_e32 v228, 16, v87
	v_and_b32_e32 v229, 0xffff0000, v87
	v_mul_f32_e32 v144, v214, v214
	v_fmac_f32_e32 v144, v215, v215
	v_fmac_f32_e32 v144, v216, v216
	v_fmac_f32_e32 v144, v217, v217
	v_fmac_f32_e32 v144, v218, v218
	v_fmac_f32_e32 v144, v219, v219
	v_fmac_f32_e32 v144, v220, v220
	v_fmac_f32_e32 v144, v221, v221
	v_mul_f32_e32 v145, v222, v222
	v_fmac_f32_e32 v145, v223, v223
	v_fmac_f32_e32 v145, v224, v224
	v_fmac_f32_e32 v145, v225, v225
	v_fmac_f32_e32 v145, v226, v226
	v_fmac_f32_e32 v145, v227, v227
	v_fmac_f32_e32 v145, v228, v228
	v_fmac_f32_e32 v145, v229, v229
	v_lshlrev_b32_e32 v240, 16, v88
	v_and_b32_e32 v241, 0xffff0000, v88
	v_lshlrev_b32_e32 v242, 16, v89
	v_and_b32_e32 v243, 0xffff0000, v89
	v_lshlrev_b32_e32 v244, 16, v90
	v_and_b32_e32 v245, 0xffff0000, v90
	v_lshlrev_b32_e32 v246, 16, v91
	v_and_b32_e32 v247, 0xffff0000, v91
	v_lshlrev_b32_e32 v248, 16, v92
	v_and_b32_e32 v249, 0xffff0000, v92
	v_lshlrev_b32_e32 v250, 16, v93
	v_and_b32_e32 v251, 0xffff0000, v93
	v_lshlrev_b32_e32 v252, 16, v94
	v_and_b32_e32 v253, 0xffff0000, v94
	v_lshlrev_b32_e32 v254, 16, v95
	v_and_b32_e32 v255, 0xffff0000, v95
	s_nop 1
	v_add_f32_dpp v144, v144, v144 quad_perm:[1,0,3,2] row_mask:0xf bank_mask:0xf
	v_add_f32_dpp v145, v145, v145 quad_perm:[1,0,3,2] row_mask:0xf bank_mask:0xf
	s_nop 1
	v_add_f32_dpp v144, v144, v144 quad_perm:[2,3,0,1] row_mask:0xf bank_mask:0xf
	v_add_f32_dpp v145, v145, v145 quad_perm:[2,3,0,1] row_mask:0xf bank_mask:0xf
	s_nop 1
	v_add_f32_dpp v144, v144, v144 row_ror:4 row_mask:0xf bank_mask:0xf
	v_add_f32_dpp v145, v145, v145 row_ror:4 row_mask:0xf bank_mask:0xf
	s_nop 1
	v_add_f32_dpp v144, v144, v144 row_ror:8 row_mask:0xf bank_mask:0xf
	v_add_f32_dpp v145, v145, v145 row_ror:8 row_mask:0xf bank_mask:0xf
	v_fmamk_f32 v144, v144, 0x3c000000, v15
	v_fmamk_f32 v145, v145, 0x3c000000, v15
	v_rsq_f32_e32 v144, v144
	v_rsq_f32_e32 v145, v145
	v_mul_f32_e32 v148, 0xbfb8aa3b, v240
	v_mul_f32_e32 v149, 0xbfb8aa3b, v241
	v_mul_f32_e32 v150, 0xbfb8aa3b, v242
	v_mul_f32_e32 v151, 0xbfb8aa3b, v243
	v_mul_f32_e32 v4, 0xbfb8aa3b, v244
	v_mul_f32_e32 v5, 0xbfb8aa3b, v245
	v_mul_f32_e32 v6, 0xbfb8aa3b, v246
	v_mul_f32_e32 v7, 0xbfb8aa3b, v247
	v_exp_f32_e32 v148, v148
	v_exp_f32_e32 v149, v149
	v_exp_f32_e32 v150, v150
	v_exp_f32_e32 v151, v151
	v_exp_f32_e32 v4, v4
	v_exp_f32_e32 v5, v5
	v_exp_f32_e32 v6, v6
	v_exp_f32_e32 v7, v7
	v_add_f32_e32 v148, 1.0, v148
	v_add_f32_e32 v149, 1.0, v149
	v_add_f32_e32 v150, 1.0, v150
	v_add_f32_e32 v151, 1.0, v151
	v_add_f32_e32 v4, 1.0, v4
	v_add_f32_e32 v5, 1.0, v5
	v_add_f32_e32 v6, 1.0, v6
	v_add_f32_e32 v7, 1.0, v7
	v_rcp_f32_e32 v148, v148
	v_rcp_f32_e32 v149, v149
	v_rcp_f32_e32 v150, v150
	v_rcp_f32_e32 v151, v151
	v_rcp_f32_e32 v4, v4
	v_rcp_f32_e32 v5, v5
	v_rcp_f32_e32 v6, v6
	v_rcp_f32_e32 v7, v7
	v_mul_f32_e32 v240, v148, v240
	v_mul_f32_e32 v241, v149, v241
	v_mul_f32_e32 v242, v150, v242
	v_mul_f32_e32 v243, v151, v243
	v_mul_f32_e32 v244, v4, v244
	v_mul_f32_e32 v245, v5, v245
	v_mul_f32_e32 v246, v6, v246
	v_mul_f32_e32 v247, v7, v247
	v_mul_f32_e32 v148, 0xbfb8aa3b, v248
	v_mul_f32_e32 v149, 0xbfb8aa3b, v249
	v_mul_f32_e32 v150, 0xbfb8aa3b, v250
	v_mul_f32_e32 v151, 0xbfb8aa3b, v251
	v_mul_f32_e32 v4, 0xbfb8aa3b, v252
	v_mul_f32_e32 v5, 0xbfb8aa3b, v253
	v_mul_f32_e32 v6, 0xbfb8aa3b, v254
	v_mul_f32_e32 v7, 0xbfb8aa3b, v255
	v_exp_f32_e32 v148, v148
	v_exp_f32_e32 v149, v149
	v_exp_f32_e32 v150, v150
	v_exp_f32_e32 v151, v151
	v_exp_f32_e32 v4, v4
	v_exp_f32_e32 v5, v5
	v_exp_f32_e32 v6, v6
	v_exp_f32_e32 v7, v7
	v_add_f32_e32 v148, 1.0, v148
	v_add_f32_e32 v149, 1.0, v149
	v_add_f32_e32 v150, 1.0, v150
	v_add_f32_e32 v151, 1.0, v151
	v_add_f32_e32 v4, 1.0, v4
	v_add_f32_e32 v5, 1.0, v5
	v_add_f32_e32 v6, 1.0, v6
	v_add_f32_e32 v7, 1.0, v7
	v_rcp_f32_e32 v148, v148
	v_rcp_f32_e32 v149, v149
	v_rcp_f32_e32 v150, v150
	v_rcp_f32_e32 v151, v151
	v_rcp_f32_e32 v4, v4
	v_rcp_f32_e32 v5, v5
	v_rcp_f32_e32 v6, v6
	v_rcp_f32_e32 v7, v7
	v_mul_f32_e32 v248, v148, v248
	v_mul_f32_e32 v249, v149, v249
	v_mul_f32_e32 v250, v150, v250
	v_mul_f32_e32 v251, v151, v251
	v_mul_f32_e32 v252, v4, v252
	v_mul_f32_e32 v253, v5, v253
	v_mul_f32_e32 v254, v6, v254
	v_mul_f32_e32 v255, v7, v255
	v_mul_f32_e32 v214, v144, v214
	v_mul_f32_e32 v215, v144, v215
	v_mul_f32_e32 v216, v144, v216
	v_mul_f32_e32 v217, v144, v217
	v_mul_f32_e32 v218, v144, v218
	v_mul_f32_e32 v219, v144, v219
	v_mul_f32_e32 v220, v144, v220
	v_mul_f32_e32 v221, v144, v221
	v_mul_f32_e32 v222, v145, v222
	v_mul_f32_e32 v223, v145, v223
	v_mul_f32_e32 v224, v145, v224
	v_mul_f32_e32 v225, v145, v225
	v_mul_f32_e32 v226, v145, v226
	v_mul_f32_e32 v227, v145, v227
	v_mul_f32_e32 v228, v145, v228
	v_mul_f32_e32 v229, v145, v229
	v_mul_f32_e32 v214, v16, v214
	v_mul_f32_e32 v215, v17, v215
	v_mul_f32_e32 v216, v18, v216
	v_mul_f32_e32 v217, v19, v217
	v_mul_f32_e32 v218, v20, v218
	v_mul_f32_e32 v219, v21, v219
	v_mul_f32_e32 v220, v22, v220
	v_mul_f32_e32 v221, v23, v221
	v_mul_f32_e32 v222, v24, v222
	v_mul_f32_e32 v223, v25, v223
	v_mul_f32_e32 v224, v26, v224
	v_mul_f32_e32 v225, v27, v225
	v_mul_f32_e32 v226, v28, v226
	v_mul_f32_e32 v227, v29, v227
	v_mul_f32_e32 v228, v30, v228
	v_mul_f32_e32 v229, v31, v229
	v_mul_f32_e32 v214, v240, v214
	v_mul_f32_e32 v215, v241, v215
	v_mul_f32_e32 v216, v242, v216
	v_mul_f32_e32 v217, v243, v217
	v_mul_f32_e32 v218, v244, v218
	v_mul_f32_e32 v219, v245, v219
	v_mul_f32_e32 v220, v246, v220
	v_mul_f32_e32 v221, v247, v221
	v_mul_f32_e32 v222, v248, v222
	v_mul_f32_e32 v223, v249, v223
	v_mul_f32_e32 v224, v250, v224
	v_mul_f32_e32 v225, v251, v225
	v_mul_f32_e32 v226, v252, v226
	v_mul_f32_e32 v227, v253, v227
	v_mul_f32_e32 v228, v254, v228
	v_mul_f32_e32 v229, v255, v229
	v_cvt_pk_bf16_f32 v144, v214, v215
	v_cvt_pk_bf16_f32 v145, v216, v217
	v_cvt_pk_bf16_f32 v146, v218, v219
	v_cvt_pk_bf16_f32 v147, v220, v221
	v_cvt_pk_bf16_f32 v148, v222, v223
	v_cvt_pk_bf16_f32 v149, v224, v225
	v_cvt_pk_bf16_f32 v150, v226, v227
	v_cvt_pk_bf16_f32 v151, v228, v229
	s_mul_i32 s9, s46, 3
	s_add_i32 s9, s9, s8
	s_lshl_b32 s3, s9, 11
	s_add_u32 s24, s16, s3
	s_addc_u32 s25, s17, 0
	global_store_dwordx4 v2, v[144:147], s[24:25]
	global_store_dwordx4 v2, v[148:151], s[24:25] offset:1024
	s_waitcnt vmcnt(20)
; DI unsigned pk_bf16(float a, float b) { f32x2 v = {a, b}; bf2_t r = __builtin_convertvector(v, bf2_t); return __builtin_bit_cast(unsigned, r); }
; DI float bflo(unsigned u) { return __uint_as_float(u << 16); }
; DI float bfhi(unsigned u) { return __uint_as_float(u & 0xffff0000u); }
; DI float silu_f(float x) { return x * __builtin_amdgcn_rcpf(1.f + __expf(-x)); }
; DI void phase_gdn_gate(const Params& p) {
;     ...
;     for (int tok = gw; tok < T_TOK; tok += nw) {
;         const u32x4 a0 = *(const u32x4*)(oraw + (size_t)tok * 1024 + 16 * lane), a1 = *(const u32x4*)(oraw + (size_t)tok * 1024 + 16 * lane + 8);
;         const u32x4 z0 = *(const u32x4*)(P0 + (size_t)tok * LDP0 + 3072 + 16 * lane), z1 = *(const u32x4*)(P0 + (size_t)tok * LDP0 + 3072 + 16 * lane + 8);
;         float o[16], z[16];
;         const unsigned au[8] = {a0.x, a0.y, a0.z, a0.w, a1.x, a1.y, a1.z, a1.w}, zu[8] = {z0.x, z0.y, z0.z, z0.w, z1.x, z1.y, z1.z, z1.w};
;         float ss = 0.f;
; #pragma unroll
;         for (int i = 0; i < 8; ++i) { o[2 * i] = bflo(au[i]); o[2 * i + 1] = bfhi(au[i]); z[2 * i] = bflo(zu[i]); z[2 * i + 1] = bfhi(zu[i]); ss += o[2 * i] * o[2 * i] + o[2 * i + 1] * o[2 * i + 1]; }
;         ss += __shfl_xor(ss, 1); ss += __shfl_xor(ss, 2); ss += __shfl_xor(ss, 4);
;         const float rstd = rsqrtf(ss * (1.f / 128.f) + 1e-6f);
;         const int d0 = (16 * lane) & 127;
;         unsigned r[8];
; #pragma unroll
;         for (int i = 0; i < 8; ++i) { const float v0 = o[2 * i] * rstd * p.onorm_a[d0 + 2 * i] * silu_f(z[2 * i]), v1 = o[2 * i + 1] * rstd * p.onorm_a[d0 + 2 * i + 1] * silu_f(z[2 * i + 1]); r[i] = pk_bf16(v0, v1); }
;         *(u32x4*)(og + (size_t)tok * 1024 + 16 * lane) = (u32x4){r[0], r[1], r[2], r[3]};
;         *(u32x4*)(og + (size_t)tok * 1024 + 16 * lane + 8) = (u32x4){r[4], r[5], r[6], r[7]};
	v_lshlrev_b32_e32 v214, 16, v96
	v_and_b32_e32 v215, 0xffff0000, v96
	v_lshlrev_b32_e32 v216, 16, v97
	v_and_b32_e32 v217, 0xffff0000, v97
	v_lshlrev_b32_e32 v218, 16, v98
	v_and_b32_e32 v219, 0xffff0000, v98
	v_lshlrev_b32_e32 v220, 16, v99
	v_and_b32_e32 v221, 0xffff0000, v99
	v_lshlrev_b32_e32 v222, 16, v100
	v_and_b32_e32 v223, 0xffff0000, v100
	v_lshlrev_b32_e32 v224, 16, v101
	v_and_b32_e32 v225, 0xffff0000, v101
	v_lshlrev_b32_e32 v226, 16, v102
	v_and_b32_e32 v227, 0xffff0000, v102
	v_lshlrev_b32_e32 v228, 16, v103
	v_and_b32_e32 v229, 0xffff0000, v103
	v_mul_f32_e32 v144, v214, v214
	v_fmac_f32_e32 v144, v215, v215
	v_fmac_f32_e32 v144, v216, v216
	v_fmac_f32_e32 v144, v217, v217
	v_fmac_f32_e32 v144, v218, v218
	v_fmac_f32_e32 v144, v219, v219
	v_fmac_f32_e32 v144, v220, v220
	v_fmac_f32_e32 v144, v221, v221
	v_mul_f32_e32 v145, v222, v222
	v_fmac_f32_e32 v145, v223, v223
	v_fmac_f32_e32 v145, v224, v224
	v_fmac_f32_e32 v145, v225, v225
	v_fmac_f32_e32 v145, v226, v226
	v_fmac_f32_e32 v145, v227, v227
	v_fmac_f32_e32 v145, v228, v228
	v_fmac_f32_e32 v145, v229, v229
	v_lshlrev_b32_e32 v240, 16, v104
	v_and_b32_e32 v241, 0xffff0000, v104
	v_lshlrev_b32_e32 v242, 16, v105
	v_and_b32_e32 v243, 0xffff0000, v105
	v_lshlrev_b32_e32 v244, 16, v106
	v_and_b32_e32 v245, 0xffff0000, v106
	v_lshlrev_b32_e32 v246, 16, v107
	v_and_b32_e32 v247, 0xffff0000, v107
	v_lshlrev_b32_e32 v248, 16, v108
	v_and_b32_e32 v249, 0xffff0000, v108
	v_lshlrev_b32_e32 v250, 16, v109
	v_and_b32_e32 v251, 0xffff0000, v109
	v_lshlrev_b32_e32 v252, 16, v110
	v_and_b32_e32 v253, 0xffff0000, v110
	v_lshlrev_b32_e32 v254, 16, v111
	v_and_b32_e32 v255, 0xffff0000, v111
	s_nop 1
	v_add_f32_dpp v144, v144, v144 quad_perm:[1,0,3,2] row_mask:0xf bank_mask:0xf
	v_add_f32_dpp v145, v145, v145 quad_perm:[1,0,3,2] row_mask:0xf bank_mask:0xf
	s_nop 1
	v_add_f32_dpp v144, v144, v144 quad_perm:[2,3,0,1] row_mask:0xf bank_mask:0xf
	v_add_f32_dpp v145, v145, v145 quad_perm:[2,3,0,1] row_mask:0xf bank_mask:0xf
	s_nop 1
	v_add_f32_dpp v144, v144, v144 row_ror:4 row_mask:0xf bank_mask:0xf
	v_add_f32_dpp v145, v145, v145 row_ror:4 row_mask:0xf bank_mask:0xf
	s_nop 1
	v_add_f32_dpp v144, v144, v144 row_ror:8 row_mask:0xf bank_mask:0xf
	v_add_f32_dpp v145, v145, v145 row_ror:8 row_mask:0xf bank_mask:0xf
	v_fmamk_f32 v144, v144, 0x3c000000, v15
	v_fmamk_f32 v145, v145, 0x3c000000, v15
	v_rsq_f32_e32 v144, v144
	v_rsq_f32_e32 v145, v145
	v_mul_f32_e32 v148, 0xbfb8aa3b, v240
	v_mul_f32_e32 v149, 0xbfb8aa3b, v241
	v_mul_f32_e32 v150, 0xbfb8aa3b, v242
	v_mul_f32_e32 v151, 0xbfb8aa3b, v243
	v_mul_f32_e32 v4, 0xbfb8aa3b, v244
	v_mul_f32_e32 v5, 0xbfb8aa3b, v245
	v_mul_f32_e32 v6, 0xbfb8aa3b, v246
	v_mul_f32_e32 v7, 0xbfb8aa3b, v247
	v_exp_f32_e32 v148, v148
	v_exp_f32_e32 v149, v149
	v_exp_f32_e32 v150, v150
	v_exp_f32_e32 v151, v151
	v_exp_f32_e32 v4, v4
	v_exp_f32_e32 v5, v5
	v_exp_f32_e32 v6, v6
	v_exp_f32_e32 v7, v7
	v_add_f32_e32 v148, 1.0, v148
	v_add_f32_e32 v149, 1.0, v149
	v_add_f32_e32 v150, 1.0, v150
	v_add_f32_e32 v151, 1.0, v151
	v_add_f32_e32 v4, 1.0, v4
	v_add_f32_e32 v5, 1.0, v5
	v_add_f32_e32 v6, 1.0, v6
	v_add_f32_e32 v7, 1.0, v7
	v_rcp_f32_e32 v148, v148
	v_rcp_f32_e32 v149, v149
	v_rcp_f32_e32 v150, v150
	v_rcp_f32_e32 v151, v151
	v_rcp_f32_e32 v4, v4
	v_rcp_f32_e32 v5, v5
	v_rcp_f32_e32 v6, v6
	v_rcp_f32_e32 v7, v7
	v_mul_f32_e32 v240, v148, v240
	v_mul_f32_e32 v241, v149, v241
	v_mul_f32_e32 v242, v150, v242
	v_mul_f32_e32 v243, v151, v243
	v_mul_f32_e32 v244, v4, v244
	v_mul_f32_e32 v245, v5, v245
	v_mul_f32_e32 v246, v6, v246
	v_mul_f32_e32 v247, v7, v247
	v_mul_f32_e32 v148, 0xbfb8aa3b, v248
	v_mul_f32_e32 v149, 0xbfb8aa3b, v249
	v_mul_f32_e32 v150, 0xbfb8aa3b, v250
	v_mul_f32_e32 v151, 0xbfb8aa3b, v251
	v_mul_f32_e32 v4, 0xbfb8aa3b, v252
	v_mul_f32_e32 v5, 0xbfb8aa3b, v253
	v_mul_f32_e32 v6, 0xbfb8aa3b, v254
	v_mul_f32_e32 v7, 0xbfb8aa3b, v255
	v_exp_f32_e32 v148, v148
	v_exp_f32_e32 v149, v149
	v_exp_f32_e32 v150, v150
	v_exp_f32_e32 v151, v151
	v_exp_f32_e32 v4, v4
	v_exp_f32_e32 v5, v5
	v_exp_f32_e32 v6, v6
	v_exp_f32_e32 v7, v7
	v_add_f32_e32 v148, 1.0, v148
	v_add_f32_e32 v149, 1.0, v149
	v_add_f32_e32 v150, 1.0, v150
	v_add_f32_e32 v151, 1.0, v151
	v_add_f32_e32 v4, 1.0, v4
	v_add_f32_e32 v5, 1.0, v5
	v_add_f32_e32 v6, 1.0, v6
	v_add_f32_e32 v7, 1.0, v7
	v_rcp_f32_e32 v148, v148
	v_rcp_f32_e32 v149, v149
	v_rcp_f32_e32 v150, v150
	v_rcp_f32_e32 v151, v151
	v_rcp_f32_e32 v4, v4
	v_rcp_f32_e32 v5, v5
	v_rcp_f32_e32 v6, v6
	v_rcp_f32_e32 v7, v7
	v_mul_f32_e32 v248, v148, v248
	v_mul_f32_e32 v249, v149, v249
	v_mul_f32_e32 v250, v150, v250
	v_mul_f32_e32 v251, v151, v251
	v_mul_f32_e32 v252, v4, v252
	v_mul_f32_e32 v253, v5, v253
	v_mul_f32_e32 v254, v6, v254
	v_mul_f32_e32 v255, v7, v255
	v_mul_f32_e32 v214, v144, v214
	v_mul_f32_e32 v215, v144, v215
	v_mul_f32_e32 v216, v144, v216
	v_mul_f32_e32 v217, v144, v217
	v_mul_f32_e32 v218, v144, v218
	v_mul_f32_e32 v219, v144, v219
	v_mul_f32_e32 v220, v144, v220
	v_mul_f32_e32 v221, v144, v221
	v_mul_f32_e32 v222, v145, v222
	v_mul_f32_e32 v223, v145, v223
	v_mul_f32_e32 v224, v145, v224
	v_mul_f32_e32 v225, v145, v225
	v_mul_f32_e32 v226, v145, v226
	v_mul_f32_e32 v227, v145, v227
	v_mul_f32_e32 v228, v145, v228
	v_mul_f32_e32 v229, v145, v229
	v_mul_f32_e32 v214, v16, v214
	v_mul_f32_e32 v215, v17, v215
	v_mul_f32_e32 v216, v18, v216
	v_mul_f32_e32 v217, v19, v217
	v_mul_f32_e32 v218, v20, v218
	v_mul_f32_e32 v219, v21, v219
	v_mul_f32_e32 v220, v22, v220
	v_mul_f32_e32 v221, v23, v221
	v_mul_f32_e32 v222, v24, v222
	v_mul_f32_e32 v223, v25, v223
	v_mul_f32_e32 v224, v26, v224
	v_mul_f32_e32 v225, v27, v225
	v_mul_f32_e32 v226, v28, v226
	v_mul_f32_e32 v227, v29, v227
	v_mul_f32_e32 v228, v30, v228
	v_mul_f32_e32 v229, v31, v229
	v_mul_f32_e32 v214, v240, v214
	v_mul_f32_e32 v215, v241, v215
	v_mul_f32_e32 v216, v242, v216
	v_mul_f32_e32 v217, v243, v217
	v_mul_f32_e32 v218, v244, v218
	v_mul_f32_e32 v219, v245, v219
	v_mul_f32_e32 v220, v246, v220
	v_mul_f32_e32 v221, v247, v221
	v_mul_f32_e32 v222, v248, v222
	v_mul_f32_e32 v223, v249, v223
	v_mul_f32_e32 v224, v250, v224
	v_mul_f32_e32 v225, v251, v225
	v_mul_f32_e32 v226, v252, v226
	v_mul_f32_e32 v227, v253, v227
	v_mul_f32_e32 v228, v254, v228
	v_mul_f32_e32 v229, v255, v229
	v_cvt_pk_bf16_f32 v144, v214, v215
	v_cvt_pk_bf16_f32 v145, v216, v217
	v_cvt_pk_bf16_f32 v146, v218, v219
	v_cvt_pk_bf16_f32 v147, v220, v221
	v_cvt_pk_bf16_f32 v148, v222, v223
	v_cvt_pk_bf16_f32 v149, v224, v225
	v_cvt_pk_bf16_f32 v150, v226, v227
	v_cvt_pk_bf16_f32 v151, v228, v229
	s_mul_i32 s9, s46, 4
	s_add_i32 s9, s9, s8
	s_lshl_b32 s3, s9, 11
	s_add_u32 s24, s16, s3
	s_addc_u32 s25, s17, 0
	global_store_dwordx4 v2, v[144:147], s[24:25]
	global_store_dwordx4 v2, v[148:151], s[24:25] offset:1024
	s_waitcnt vmcnt(18)
; DI unsigned pk_bf16(float a, float b) { f32x2 v = {a, b}; bf2_t r = __builtin_convertvector(v, bf2_t); return __builtin_bit_cast(unsigned, r); }
; DI float bflo(unsigned u) { return __uint_as_float(u << 16); }
; DI float bfhi(unsigned u) { return __uint_as_float(u & 0xffff0000u); }
; DI float silu_f(float x) { return x * __builtin_amdgcn_rcpf(1.f + __expf(-x)); }
; DI void phase_gdn_gate(const Params& p) {
;     ...
;     for (int tok = gw; tok < T_TOK; tok += nw) {
;         const u32x4 a0 = *(const u32x4*)(oraw + (size_t)tok * 1024 + 16 * lane), a1 = *(const u32x4*)(oraw + (size_t)tok * 1024 + 16 * lane + 8);
;         const u32x4 z0 = *(const u32x4*)(P0 + (size_t)tok * LDP0 + 3072 + 16 * lane), z1 = *(const u32x4*)(P0 + (size_t)tok * LDP0 + 3072 + 16 * lane + 8);
;         float o[16], z[16];
;         const unsigned au[8] = {a0.x, a0.y, a0.z, a0.w, a1.x, a1.y, a1.z, a1.w}, zu[8] = {z0.x, z0.y, z0.z, z0.w, z1.x, z1.y, z1.z, z1.w};
;         float ss = 0.f;
; #pragma unroll
;         for (int i = 0; i < 8; ++i) { o[2 * i] = bflo(au[i]); o[2 * i + 1] = bfhi(au[i]); z[2 * i] = bflo(zu[i]); z[2 * i + 1] = bfhi(zu[i]); ss += o[2 * i] * o[2 * i] + o[2 * i + 1] * o[2 * i + 1]; }
;         ss += __shfl_xor(ss, 1); ss += __shfl_xor(ss, 2); ss += __shfl_xor(ss, 4);
;         const float rstd = rsqrtf(ss * (1.f / 128.f) + 1e-6f);
;         const int d0 = (16 * lane) & 127;
;         unsigned r[8];
; #pragma unroll
;         for (int i = 0; i < 8; ++i) { const float v0 = o[2 * i] * rstd * p.onorm_a[d0 + 2 * i] * silu_f(z[2 * i]), v1 = o[2 * i + 1] * rstd * p.onorm_a[d0 + 2 * i + 1] * silu_f(z[2 * i + 1]); r[i] = pk_bf16(v0, v1); }
;         *(u32x4*)(og + (size_t)tok * 1024 + 16 * lane) = (u32x4){r[0], r[1], r[2], r[3]};
;         *(u32x4*)(og + (size_t)tok * 1024 + 16 * lane + 8) = (u32x4){r[4], r[5], r[6], r[7]};
	v_lshlrev_b32_e32 v214, 16, v112
	v_and_b32_e32 v215, 0xffff0000, v112
	v_lshlrev_b32_e32 v216, 16, v113
	v_and_b32_e32 v217, 0xffff0000, v113
	v_lshlrev_b32_e32 v218, 16, v114
	v_and_b32_e32 v219, 0xffff0000, v114
	v_lshlrev_b32_e32 v220, 16, v115
	v_and_b32_e32 v221, 0xffff0000, v115
	v_lshlrev_b32_e32 v222, 16, v116
	v_and_b32_e32 v223, 0xffff0000, v116
	v_lshlrev_b32_e32 v224, 16, v117
	v_and_b32_e32 v225, 0xffff0000, v117
	v_lshlrev_b32_e32 v226, 16, v118
	v_and_b32_e32 v227, 0xffff0000, v118
	v_lshlrev_b32_e32 v228, 16, v119
	v_and_b32_e32 v229, 0xffff0000, v119
	v_mul_f32_e32 v144, v214, v214
	v_fmac_f32_e32 v144, v215, v215
	v_fmac_f32_e32 v144, v216, v216
	v_fmac_f32_e32 v144, v217, v217
	v_fmac_f32_e32 v144, v218, v218
	v_fmac_f32_e32 v144, v219, v219
	v_fmac_f32_e32 v144, v220, v220
	v_fmac_f32_e32 v144, v221, v221
	v_mul_f32_e32 v145, v222, v222
	v_fmac_f32_e32 v145, v223, v223
	v_fmac_f32_e32 v145, v224, v224
	v_fmac_f32_e32 v145, v225, v225
	v_fmac_f32_e32 v145, v226, v226
	v_fmac_f32_e32 v145, v227, v227
	v_fmac_f32_e32 v145, v228, v228
	v_fmac_f32_e32 v145, v229, v229
	v_lshlrev_b32_e32 v240, 16, v120
	v_and_b32_e32 v241, 0xffff0000, v120
	v_lshlrev_b32_e32 v242, 16, v121
	v_and_b32_e32 v243, 0xffff0000, v121
	v_lshlrev_b32_e32 v244, 16, v122
	v_and_b32_e32 v245, 0xffff0000, v122
	v_lshlrev_b32_e32 v246, 16, v123
	v_and_b32_e32 v247, 0xffff0000, v123
	v_lshlrev_b32_e32 v248, 16, v124
	v_and_b32_e32 v249, 0xffff0000, v124
	v_lshlrev_b32_e32 v250, 16, v125
	v_and_b32_e32 v251, 0xffff0000, v125
	v_lshlrev_b32_e32 v252, 16, v126
	v_and_b32_e32 v253, 0xffff0000, v126
	v_lshlrev_b32_e32 v254, 16, v127
	v_and_b32_e32 v255, 0xffff0000, v127
	s_nop 1
	v_add_f32_dpp v144, v144, v144 quad_perm:[1,0,3,2] row_mask:0xf bank_mask:0xf
	v_add_f32_dpp v145, v145, v145 quad_perm:[1,0,3,2] row_mask:0xf bank_mask:0xf
	s_nop 1
	v_add_f32_dpp v144, v144, v144 quad_perm:[2,3,0,1] row_mask:0xf bank_mask:0xf
	v_add_f32_dpp v145, v145, v145 quad_perm:[2,3,0,1] row_mask:0xf bank_mask:0xf
	s_nop 1
	v_add_f32_dpp v144, v144, v144 row_ror:4 row_mask:0xf bank_mask:0xf
	v_add_f32_dpp v145, v145, v145 row_ror:4 row_mask:0xf bank_mask:0xf
	s_nop 1
	v_add_f32_dpp v144, v144, v144 row_ror:8 row_mask:0xf bank_mask:0xf
	v_add_f32_dpp v145, v145, v145 row_ror:8 row_mask:0xf bank_mask:0xf
	v_fmamk_f32 v144, v144, 0x3c000000, v15
	v_fmamk_f32 v145, v145, 0x3c000000, v15
	v_rsq_f32_e32 v144, v144
	v_rsq_f32_e32 v145, v145
	v_mul_f32_e32 v148, 0xbfb8aa3b, v240
	v_mul_f32_e32 v149, 0xbfb8aa3b, v241
	v_mul_f32_e32 v150, 0xbfb8aa3b, v242
	v_mul_f32_e32 v151, 0xbfb8aa3b, v243
	v_mul_f32_e32 v4, 0xbfb8aa3b, v244
	v_mul_f32_e32 v5, 0xbfb8aa3b, v245
	v_mul_f32_e32 v6, 0xbfb8aa3b, v246
	v_mul_f32_e32 v7, 0xbfb8aa3b, v247
	v_exp_f32_e32 v148, v148
	v_exp_f32_e32 v149, v149
	v_exp_f32_e32 v150, v150
	v_exp_f32_e32 v151, v151
	v_exp_f32_e32 v4, v4
	v_exp_f32_e32 v5, v5
	v_exp_f32_e32 v6, v6
	v_exp_f32_e32 v7, v7
	v_add_f32_e32 v148, 1.0, v148
	v_add_f32_e32 v149, 1.0, v149
	v_add_f32_e32 v150, 1.0, v150
	v_add_f32_e32 v151, 1.0, v151
	v_add_f32_e32 v4, 1.0, v4
	v_add_f32_e32 v5, 1.0, v5
	v_add_f32_e32 v6, 1.0, v6
	v_add_f32_e32 v7, 1.0, v7
	v_rcp_f32_e32 v148, v148
	v_rcp_f32_e32 v149, v149
	v_rcp_f32_e32 v150, v150
	v_rcp_f32_e32 v151, v151
	v_rcp_f32_e32 v4, v4
	v_rcp_f32_e32 v5, v5
	v_rcp_f32_e32 v6, v6
	v_rcp_f32_e32 v7, v7
	v_mul_f32_e32 v240, v148, v240
	v_mul_f32_e32 v241, v149, v241
	v_mul_f32_e32 v242, v150, v242
	v_mul_f32_e32 v243, v151, v243
	v_mul_f32_e32 v244, v4, v244
	v_mul_f32_e32 v245, v5, v245
	v_mul_f32_e32 v246, v6, v246
	v_mul_f32_e32 v247, v7, v247
	v_mul_f32_e32 v148, 0xbfb8aa3b, v248
	v_mul_f32_e32 v149, 0xbfb8aa3b, v249
	v_mul_f32_e32 v150, 0xbfb8aa3b, v250
	v_mul_f32_e32 v151, 0xbfb8aa3b, v251
	v_mul_f32_e32 v4, 0xbfb8aa3b, v252
	v_mul_f32_e32 v5, 0xbfb8aa3b, v253
	v_mul_f32_e32 v6, 0xbfb8aa3b, v254
	v_mul_f32_e32 v7, 0xbfb8aa3b, v255
	v_exp_f32_e32 v148, v148
	v_exp_f32_e32 v149, v149
	v_exp_f32_e32 v150, v150
	v_exp_f32_e32 v151, v151
	v_exp_f32_e32 v4, v4
	v_exp_f32_e32 v5, v5
	v_exp_f32_e32 v6, v6
	v_exp_f32_e32 v7, v7
	v_add_f32_e32 v148, 1.0, v148
	v_add_f32_e32 v149, 1.0, v149
	v_add_f32_e32 v150, 1.0, v150
	v_add_f32_e32 v151, 1.0, v151
	v_add_f32_e32 v4, 1.0, v4
	v_add_f32_e32 v5, 1.0, v5
	v_add_f32_e32 v6, 1.0, v6
	v_add_f32_e32 v7, 1.0, v7
	v_rcp_f32_e32 v148, v148
	v_rcp_f32_e32 v149, v149
	v_rcp_f32_e32 v150, v150
	v_rcp_f32_e32 v151, v151
	v_rcp_f32_e32 v4, v4
	v_rcp_f32_e32 v5, v5
	v_rcp_f32_e32 v6, v6
	v_rcp_f32_e32 v7, v7
	v_mul_f32_e32 v248, v148, v248
	v_mul_f32_e32 v249, v149, v249
	v_mul_f32_e32 v250, v150, v250
	v_mul_f32_e32 v251, v151, v251
	v_mul_f32_e32 v252, v4, v252
	v_mul_f32_e32 v253, v5, v253
	v_mul_f32_e32 v254, v6, v254
	v_mul_f32_e32 v255, v7, v255
	v_mul_f32_e32 v214, v144, v214
	v_mul_f32_e32 v215, v144, v215
	v_mul_f32_e32 v216, v144, v216
	v_mul_f32_e32 v217, v144, v217
	v_mul_f32_e32 v218, v144, v218
	v_mul_f32_e32 v219, v144, v219
	v_mul_f32_e32 v220, v144, v220
	v_mul_f32_e32 v221, v144, v221
	v_mul_f32_e32 v222, v145, v222
	v_mul_f32_e32 v223, v145, v223
	v_mul_f32_e32 v224, v145, v224
	v_mul_f32_e32 v225, v145, v225
	v_mul_f32_e32 v226, v145, v226
	v_mul_f32_e32 v227, v145, v227
	v_mul_f32_e32 v228, v145, v228
	v_mul_f32_e32 v229, v145, v229
	v_mul_f32_e32 v214, v16, v214
	v_mul_f32_e32 v215, v17, v215
	v_mul_f32_e32 v216, v18, v216
	v_mul_f32_e32 v217, v19, v217
	v_mul_f32_e32 v218, v20, v218
	v_mul_f32_e32 v219, v21, v219
	v_mul_f32_e32 v220, v22, v220
	v_mul_f32_e32 v221, v23, v221
	v_mul_f32_e32 v222, v24, v222
	v_mul_f32_e32 v223, v25, v223
	v_mul_f32_e32 v224, v26, v224
	v_mul_f32_e32 v225, v27, v225
	v_mul_f32_e32 v226, v28, v226
	v_mul_f32_e32 v227, v29, v227
	v_mul_f32_e32 v228, v30, v228
	v_mul_f32_e32 v229, v31, v229
	v_mul_f32_e32 v214, v240, v214
	v_mul_f32_e32 v215, v241, v215
	v_mul_f32_e32 v216, v242, v216
	v_mul_f32_e32 v217, v243, v217
	v_mul_f32_e32 v218, v244, v218
	v_mul_f32_e32 v219, v245, v219
	v_mul_f32_e32 v220, v246, v220
	v_mul_f32_e32 v221, v247, v221
	v_mul_f32_e32 v222, v248, v222
	v_mul_f32_e32 v223, v249, v223
	v_mul_f32_e32 v224, v250, v224
	v_mul_f32_e32 v225, v251, v225
	v_mul_f32_e32 v226, v252, v226
	v_mul_f32_e32 v227, v253, v227
	v_mul_f32_e32 v228, v254, v228
	v_mul_f32_e32 v229, v255, v229
	v_cvt_pk_bf16_f32 v144, v214, v215
	v_cvt_pk_bf16_f32 v145, v216, v217
	v_cvt_pk_bf16_f32 v146, v218, v219
	v_cvt_pk_bf16_f32 v147, v220, v221
	v_cvt_pk_bf16_f32 v148, v222, v223
	v_cvt_pk_bf16_f32 v149, v224, v225
	v_cvt_pk_bf16_f32 v150, v226, v227
	v_cvt_pk_bf16_f32 v151, v228, v229
	s_mul_i32 s9, s46, 5
	s_add_i32 s9, s9, s8
	s_lshl_b32 s3, s9, 11
	s_add_u32 s24, s16, s3
	s_addc_u32 s25, s17, 0
	global_store_dwordx4 v2, v[144:147], s[24:25]
	global_store_dwordx4 v2, v[148:151], s[24:25] offset:1024
	s_waitcnt vmcnt(16)
; DI unsigned pk_bf16(float a, float b) { f32x2 v = {a, b}; bf2_t r = __builtin_convertvector(v, bf2_t); return __builtin_bit_cast(unsigned, r); }
; DI float bflo(unsigned u) { return __uint_as_float(u << 16); }
; DI float bfhi(unsigned u) { return __uint_as_float(u & 0xffff0000u); }
; DI float silu_f(float x) { return x * __builtin_amdgcn_rcpf(1.f + __expf(-x)); }
; DI void phase_gdn_gate(const Params& p) {
;     ...
;     for (int tok = gw; tok < T_TOK; tok += nw) {
;         const u32x4 a0 = *(const u32x4*)(oraw + (size_t)tok * 1024 + 16 * lane), a1 = *(const u32x4*)(oraw + (size_t)tok * 1024 + 16 * lane + 8);
;         const u32x4 z0 = *(const u32x4*)(P0 + (size_t)tok * LDP0 + 3072 + 16 * lane), z1 = *(const u32x4*)(P0 + (size_t)tok * LDP0 + 3072 + 16 * lane + 8);
;         float o[16], z[16];
;         const unsigned au[8] = {a0.x, a0.y, a0.z, a0.w, a1.x, a1.y, a1.z, a1.w}, zu[8] = {z0.x, z0.y, z0.z, z0.w, z1.x, z1.y, z1.z, z1.w};
;         float ss = 0.f;
; #pragma unroll
;         for (int i = 0; i < 8; ++i) { o[2 * i] = bflo(au[i]); o[2 * i + 1] = bfhi(au[i]); z[2 * i] = bflo(zu[i]); z[2 * i + 1] = bfhi(zu[i]); ss += o[2 * i] * o[2 * i] + o[2 * i + 1] * o[2 * i + 1]; }
;         ss += __shfl_xor(ss, 1); ss += __shfl_xor(ss, 2); ss += __shfl_xor(ss, 4);
;         const float rstd = rsqrtf(ss * (1.f / 128.f) + 1e-6f);
;         const int d0 = (16 * lane) & 127;
;         unsigned r[8];
; #pragma unroll
;         for (int i = 0; i < 8; ++i) { const float v0 = o[2 * i] * rstd * p.onorm_a[d0 + 2 * i] * silu_f(z[2 * i]), v1 = o[2 * i + 1] * rstd * p.onorm_a[d0 + 2 * i + 1] * silu_f(z[2 * i + 1]); r[i] = pk_bf16(v0, v1); }
;         *(u32x4*)(og + (size_t)tok * 1024 + 16 * lane) = (u32x4){r[0], r[1], r[2], r[3]};
;         *(u32x4*)(og + (size_t)tok * 1024 + 16 * lane + 8) = (u32x4){r[4], r[5], r[6], r[7]};
	v_lshlrev_b32_e32 v214, 16, v128
	v_and_b32_e32 v215, 0xffff0000, v128
	v_lshlrev_b32_e32 v216, 16, v129
	v_and_b32_e32 v217, 0xffff0000, v129
	v_lshlrev_b32_e32 v218, 16, v130
	v_and_b32_e32 v219, 0xffff0000, v130
	v_lshlrev_b32_e32 v220, 16, v131
	v_and_b32_e32 v221, 0xffff0000, v131
	v_lshlrev_b32_e32 v222, 16, v132
	v_and_b32_e32 v223, 0xffff0000, v132
	v_lshlrev_b32_e32 v224, 16, v133
	v_and_b32_e32 v225, 0xffff0000, v133
	v_lshlrev_b32_e32 v226, 16, v134
	v_and_b32_e32 v227, 0xffff0000, v134
	v_lshlrev_b32_e32 v228, 16, v135
	v_and_b32_e32 v229, 0xffff0000, v135
	v_mul_f32_e32 v144, v214, v214
	v_fmac_f32_e32 v144, v215, v215
	v_fmac_f32_e32 v144, v216, v216
	v_fmac_f32_e32 v144, v217, v217
	v_fmac_f32_e32 v144, v218, v218
	v_fmac_f32_e32 v144, v219, v219
	v_fmac_f32_e32 v144, v220, v220
	v_fmac_f32_e32 v144, v221, v221
	v_mul_f32_e32 v145, v222, v222
	v_fmac_f32_e32 v145, v223, v223
	v_fmac_f32_e32 v145, v224, v224
	v_fmac_f32_e32 v145, v225, v225
	v_fmac_f32_e32 v145, v226, v226
	v_fmac_f32_e32 v145, v227, v227
	v_fmac_f32_e32 v145, v228, v228
	v_fmac_f32_e32 v145, v229, v229
	v_lshlrev_b32_e32 v240, 16, v136
	v_and_b32_e32 v241, 0xffff0000, v136
	v_lshlrev_b32_e32 v242, 16, v137
	v_and_b32_e32 v243, 0xffff0000, v137
	v_lshlrev_b32_e32 v244, 16, v138
	v_and_b32_e32 v245, 0xffff0000, v138
	v_lshlrev_b32_e32 v246, 16, v139
	v_and_b32_e32 v247, 0xffff0000, v139
	v_lshlrev_b32_e32 v248, 16, v140
	v_and_b32_e32 v249, 0xffff0000, v140
	v_lshlrev_b32_e32 v250, 16, v141
	v_and_b32_e32 v251, 0xffff0000, v141
	v_lshlrev_b32_e32 v252, 16, v142
	v_and_b32_e32 v253, 0xffff0000, v142
	v_lshlrev_b32_e32 v254, 16, v143
	v_and_b32_e32 v255, 0xffff0000, v143
	s_nop 1
	v_add_f32_dpp v144, v144, v144 quad_perm:[1,0,3,2] row_mask:0xf bank_mask:0xf
	v_add_f32_dpp v145, v145, v145 quad_perm:[1,0,3,2] row_mask:0xf bank_mask:0xf
	s_nop 1
	v_add_f32_dpp v144, v144, v144 quad_perm:[2,3,0,1] row_mask:0xf bank_mask:0xf
	v_add_f32_dpp v145, v145, v145 quad_perm:[2,3,0,1] row_mask:0xf bank_mask:0xf
	s_nop 1
	v_add_f32_dpp v144, v144, v144 row_ror:4 row_mask:0xf bank_mask:0xf
	v_add_f32_dpp v145, v145, v145 row_ror:4 row_mask:0xf bank_mask:0xf
	s_nop 1
	v_add_f32_dpp v144, v144, v144 row_ror:8 row_mask:0xf bank_mask:0xf
	v_add_f32_dpp v145, v145, v145 row_ror:8 row_mask:0xf bank_mask:0xf
	v_fmamk_f32 v144, v144, 0x3c000000, v15
	v_fmamk_f32 v145, v145, 0x3c000000, v15
	v_rsq_f32_e32 v144, v144
	v_rsq_f32_e32 v145, v145
	v_mul_f32_e32 v148, 0xbfb8aa3b, v240
	v_mul_f32_e32 v149, 0xbfb8aa3b, v241
	v_mul_f32_e32 v150, 0xbfb8aa3b, v242
	v_mul_f32_e32 v151, 0xbfb8aa3b, v243
	v_mul_f32_e32 v4, 0xbfb8aa3b, v244
	v_mul_f32_e32 v5, 0xbfb8aa3b, v245
	v_mul_f32_e32 v6, 0xbfb8aa3b, v246
	v_mul_f32_e32 v7, 0xbfb8aa3b, v247
	v_exp_f32_e32 v148, v148
	v_exp_f32_e32 v149, v149
	v_exp_f32_e32 v150, v150
	v_exp_f32_e32 v151, v151
	v_exp_f32_e32 v4, v4
	v_exp_f32_e32 v5, v5
	v_exp_f32_e32 v6, v6
	v_exp_f32_e32 v7, v7
	v_add_f32_e32 v148, 1.0, v148
	v_add_f32_e32 v149, 1.0, v149
	v_add_f32_e32 v150, 1.0, v150
	v_add_f32_e32 v151, 1.0, v151
	v_add_f32_e32 v4, 1.0, v4
	v_add_f32_e32 v5, 1.0, v5
	v_add_f32_e32 v6, 1.0, v6
	v_add_f32_e32 v7, 1.0, v7
	v_rcp_f32_e32 v148, v148
	v_rcp_f32_e32 v149, v149
	v_rcp_f32_e32 v150, v150
	v_rcp_f32_e32 v151, v151
	v_rcp_f32_e32 v4, v4
	v_rcp_f32_e32 v5, v5
	v_rcp_f32_e32 v6, v6
	v_rcp_f32_e32 v7, v7
	v_mul_f32_e32 v240, v148, v240
	v_mul_f32_e32 v241, v149, v241
	v_mul_f32_e32 v242, v150, v242
	v_mul_f32_e32 v243, v151, v243
	v_mul_f32_e32 v244, v4, v244
	v_mul_f32_e32 v245, v5, v245
	v_mul_f32_e32 v246, v6, v246
	v_mul_f32_e32 v247, v7, v247
	v_mul_f32_e32 v148, 0xbfb8aa3b, v248
	v_mul_f32_e32 v149, 0xbfb8aa3b, v249
	v_mul_f32_e32 v150, 0xbfb8aa3b, v250
	v_mul_f32_e32 v151, 0xbfb8aa3b, v251
	v_mul_f32_e32 v4, 0xbfb8aa3b, v252
	v_mul_f32_e32 v5, 0xbfb8aa3b, v253
	v_mul_f32_e32 v6, 0xbfb8aa3b, v254
	v_mul_f32_e32 v7, 0xbfb8aa3b, v255
	v_exp_f32_e32 v148, v148
	v_exp_f32_e32 v149, v149
	v_exp_f32_e32 v150, v150
	v_exp_f32_e32 v151, v151
	v_exp_f32_e32 v4, v4
	v_exp_f32_e32 v5, v5
	v_exp_f32_e32 v6, v6
	v_exp_f32_e32 v7, v7
	v_add_f32_e32 v148, 1.0, v148
	v_add_f32_e32 v149, 1.0, v149
	v_add_f32_e32 v150, 1.0, v150
	v_add_f32_e32 v151, 1.0, v151
	v_add_f32_e32 v4, 1.0, v4
	v_add_f32_e32 v5, 1.0, v5
	v_add_f32_e32 v6, 1.0, v6
	v_add_f32_e32 v7, 1.0, v7
	v_rcp_f32_e32 v148, v148
	v_rcp_f32_e32 v149, v149
	v_rcp_f32_e32 v150, v150
	v_rcp_f32_e32 v151, v151
	v_rcp_f32_e32 v4, v4
	v_rcp_f32_e32 v5, v5
	v_rcp_f32_e32 v6, v6
	v_rcp_f32_e32 v7, v7
	v_mul_f32_e32 v248, v148, v248
	v_mul_f32_e32 v249, v149, v249
	v_mul_f32_e32 v250, v150, v250
	v_mul_f32_e32 v251, v151, v251
	v_mul_f32_e32 v252, v4, v252
	v_mul_f32_e32 v253, v5, v253
	v_mul_f32_e32 v254, v6, v254
	v_mul_f32_e32 v255, v7, v255
	v_mul_f32_e32 v214, v144, v214
	v_mul_f32_e32 v215, v144, v215
	v_mul_f32_e32 v216, v144, v216
	v_mul_f32_e32 v217, v144, v217
	v_mul_f32_e32 v218, v144, v218
	v_mul_f32_e32 v219, v144, v219
	v_mul_f32_e32 v220, v144, v220
	v_mul_f32_e32 v221, v144, v221
	v_mul_f32_e32 v222, v145, v222
	v_mul_f32_e32 v223, v145, v223
	v_mul_f32_e32 v224, v145, v224
	v_mul_f32_e32 v225, v145, v225
	v_mul_f32_e32 v226, v145, v226
	v_mul_f32_e32 v227, v145, v227
	v_mul_f32_e32 v228, v145, v228
	v_mul_f32_e32 v229, v145, v229
	v_mul_f32_e32 v214, v16, v214
	v_mul_f32_e32 v215, v17, v215
	v_mul_f32_e32 v216, v18, v216
	v_mul_f32_e32 v217, v19, v217
	v_mul_f32_e32 v218, v20, v218
	v_mul_f32_e32 v219, v21, v219
	v_mul_f32_e32 v220, v22, v220
	v_mul_f32_e32 v221, v23, v221
	v_mul_f32_e32 v222, v24, v222
	v_mul_f32_e32 v223, v25, v223
	v_mul_f32_e32 v224, v26, v224
	v_mul_f32_e32 v225, v27, v225
	v_mul_f32_e32 v226, v28, v226
	v_mul_f32_e32 v227, v29, v227
	v_mul_f32_e32 v228, v30, v228
	v_mul_f32_e32 v229, v31, v229
	v_mul_f32_e32 v214, v240, v214
	v_mul_f32_e32 v215, v241, v215
	v_mul_f32_e32 v216, v242, v216
	v_mul_f32_e32 v217, v243, v217
	v_mul_f32_e32 v218, v244, v218
	v_mul_f32_e32 v219, v245, v219
	v_mul_f32_e32 v220, v246, v220
	v_mul_f32_e32 v221, v247, v221
	v_mul_f32_e32 v222, v248, v222
	v_mul_f32_e32 v223, v249, v223
	v_mul_f32_e32 v224, v250, v224
	v_mul_f32_e32 v225, v251, v225
	v_mul_f32_e32 v226, v252, v226
	v_mul_f32_e32 v227, v253, v227
	v_mul_f32_e32 v228, v254, v228
	v_mul_f32_e32 v229, v255, v229
	v_cvt_pk_bf16_f32 v144, v214, v215
	v_cvt_pk_bf16_f32 v145, v216, v217
	v_cvt_pk_bf16_f32 v146, v218, v219
	v_cvt_pk_bf16_f32 v147, v220, v221
	v_cvt_pk_bf16_f32 v148, v222, v223
	v_cvt_pk_bf16_f32 v149, v224, v225
	v_cvt_pk_bf16_f32 v150, v226, v227
	v_cvt_pk_bf16_f32 v151, v228, v229
	s_mul_i32 s9, s46, 6
	s_add_i32 s9, s9, s8
	s_lshl_b32 s3, s9, 11
	s_add_u32 s24, s16, s3
	s_addc_u32 s25, s17, 0
	global_store_dwordx4 v2, v[144:147], s[24:25]
	global_store_dwordx4 v2, v[148:151], s[24:25] offset:1024
	s_waitcnt vmcnt(14)
; DI unsigned pk_bf16(float a, float b) { f32x2 v = {a, b}; bf2_t r = __builtin_convertvector(v, bf2_t); return __builtin_bit_cast(unsigned, r); }
; DI float bflo(unsigned u) { return __uint_as_float(u << 16); }
; DI float bfhi(unsigned u) { return __uint_as_float(u & 0xffff0000u); }
; DI float silu_f(float x) { return x * __builtin_amdgcn_rcpf(1.f + __expf(-x)); }
; DI void phase_gdn_gate(const Params& p) {
;     ...
;     for (int tok = gw; tok < T_TOK; tok += nw) {
;         const u32x4 a0 = *(const u32x4*)(oraw + (size_t)tok * 1024 + 16 * lane), a1 = *(const u32x4*)(oraw + (size_t)tok * 1024 + 16 * lane + 8);
;         const u32x4 z0 = *(const u32x4*)(P0 + (size_t)tok * LDP0 + 3072 + 16 * lane), z1 = *(const u32x4*)(P0 + (size_t)tok * LDP0 + 3072 + 16 * lane + 8);
;         float o[16], z[16];
;         const unsigned au[8] = {a0.x, a0.y, a0.z, a0.w, a1.x, a1.y, a1.z, a1.w}, zu[8] = {z0.x, z0.y, z0.z, z0.w, z1.x, z1.y, z1.z, z1.w};
;         float ss = 0.f;
; #pragma unroll
;         for (int i = 0; i < 8; ++i) { o[2 * i] = bflo(au[i]); o[2 * i + 1] = bfhi(au[i]); z[2 * i] = bflo(zu[i]); z[2 * i + 1] = bfhi(zu[i]); ss += o[2 * i] * o[2 * i] + o[2 * i + 1] * o[2 * i + 1]; }
;         ss += __shfl_xor(ss, 1); ss += __shfl_xor(ss, 2); ss += __shfl_xor(ss, 4);
;         const float rstd = rsqrtf(ss * (1.f / 128.f) + 1e-6f);
;         const int d0 = (16 * lane) & 127;
;         unsigned r[8];
; #pragma unroll
;         for (int i = 0; i < 8; ++i) { const float v0 = o[2 * i] * rstd * p.onorm_a[d0 + 2 * i] * silu_f(z[2 * i]), v1 = o[2 * i + 1] * rstd * p.onorm_a[d0 + 2 * i + 1] * silu_f(z[2 * i + 1]); r[i] = pk_bf16(v0, v1); }
;         *(u32x4*)(og + (size_t)tok * 1024 + 16 * lane) = (u32x4){r[0], r[1], r[2], r[3]};
;         *(u32x4*)(og + (size_t)tok * 1024 + 16 * lane + 8) = (u32x4){r[4], r[5], r[6], r[7]};
	v_lshlrev_b32_e32 v214, 16, v168
	v_and_b32_e32 v215, 0xffff0000, v168
	v_lshlrev_b32_e32 v216, 16, v169
	v_and_b32_e32 v217, 0xffff0000, v169
	v_lshlrev_b32_e32 v218, 16, v170
	v_and_b32_e32 v219, 0xffff0000, v170
	v_lshlrev_b32_e32 v220, 16, v171
	v_and_b32_e32 v221, 0xffff0000, v171
	v_lshlrev_b32_e32 v222, 16, v172
	v_and_b32_e32 v223, 0xffff0000, v172
	v_lshlrev_b32_e32 v224, 16, v173
	v_and_b32_e32 v225, 0xffff0000, v173
	v_lshlrev_b32_e32 v226, 16, v174
	v_and_b32_e32 v227, 0xffff0000, v174
	v_lshlrev_b32_e32 v228, 16, v175
	v_and_b32_e32 v229, 0xffff0000, v175
	v_mul_f32_e32 v144, v214, v214
	v_fmac_f32_e32 v144, v215, v215
	v_fmac_f32_e32 v144, v216, v216
	v_fmac_f32_e32 v144, v217, v217
	v_fmac_f32_e32 v144, v218, v218
	v_fmac_f32_e32 v144, v219, v219
	v_fmac_f32_e32 v144, v220, v220
	v_fmac_f32_e32 v144, v221, v221
	v_mul_f32_e32 v145, v222, v222
	v_fmac_f32_e32 v145, v223, v223
	v_fmac_f32_e32 v145, v224, v224
	v_fmac_f32_e32 v145, v225, v225
	v_fmac_f32_e32 v145, v226, v226
	v_fmac_f32_e32 v145, v227, v227
	v_fmac_f32_e32 v145, v228, v228
	v_fmac_f32_e32 v145, v229, v229
	v_lshlrev_b32_e32 v240, 16, v176
	v_and_b32_e32 v241, 0xffff0000, v176
	v_lshlrev_b32_e32 v242, 16, v177
	v_and_b32_e32 v243, 0xffff0000, v177
	v_lshlrev_b32_e32 v244, 16, v178
	v_and_b32_e32 v245, 0xffff0000, v178
	v_lshlrev_b32_e32 v246, 16, v179
	v_and_b32_e32 v247, 0xffff0000, v179
	v_lshlrev_b32_e32 v248, 16, v180
	v_and_b32_e32 v249, 0xffff0000, v180
	v_lshlrev_b32_e32 v250, 16, v181
	v_and_b32_e32 v251, 0xffff0000, v181
	v_lshlrev_b32_e32 v252, 16, v182
	v_and_b32_e32 v253, 0xffff0000, v182
	v_lshlrev_b32_e32 v254, 16, v183
	v_and_b32_e32 v255, 0xffff0000, v183
	s_nop 1
	v_add_f32_dpp v144, v144, v144 quad_perm:[1,0,3,2] row_mask:0xf bank_mask:0xf
	v_add_f32_dpp v145, v145, v145 quad_perm:[1,0,3,2] row_mask:0xf bank_mask:0xf
	s_nop 1
	v_add_f32_dpp v144, v144, v144 quad_perm:[2,3,0,1] row_mask:0xf bank_mask:0xf
	v_add_f32_dpp v145, v145, v145 quad_perm:[2,3,0,1] row_mask:0xf bank_mask:0xf
	s_nop 1
	v_add_f32_dpp v144, v144, v144 row_ror:4 row_mask:0xf bank_mask:0xf
	v_add_f32_dpp v145, v145, v145 row_ror:4 row_mask:0xf bank_mask:0xf
	s_nop 1
	v_add_f32_dpp v144, v144, v144 row_ror:8 row_mask:0xf bank_mask:0xf
	v_add_f32_dpp v145, v145, v145 row_ror:8 row_mask:0xf bank_mask:0xf
	v_fmamk_f32 v144, v144, 0x3c000000, v15
	v_fmamk_f32 v145, v145, 0x3c000000, v15
	v_rsq_f32_e32 v144, v144
	v_rsq_f32_e32 v145, v145
	v_mul_f32_e32 v148, 0xbfb8aa3b, v240
	v_mul_f32_e32 v149, 0xbfb8aa3b, v241
	v_mul_f32_e32 v150, 0xbfb8aa3b, v242
	v_mul_f32_e32 v151, 0xbfb8aa3b, v243
	v_mul_f32_e32 v4, 0xbfb8aa3b, v244
	v_mul_f32_e32 v5, 0xbfb8aa3b, v245
	v_mul_f32_e32 v6, 0xbfb8aa3b, v246
	v_mul_f32_e32 v7, 0xbfb8aa3b, v247
	v_exp_f32_e32 v148, v148
	v_exp_f32_e32 v149, v149
	v_exp_f32_e32 v150, v150
	v_exp_f32_e32 v151, v151
	v_exp_f32_e32 v4, v4
	v_exp_f32_e32 v5, v5
	v_exp_f32_e32 v6, v6
	v_exp_f32_e32 v7, v7
	v_add_f32_e32 v148, 1.0, v148
	v_add_f32_e32 v149, 1.0, v149
	v_add_f32_e32 v150, 1.0, v150
	v_add_f32_e32 v151, 1.0, v151
	v_add_f32_e32 v4, 1.0, v4
	v_add_f32_e32 v5, 1.0, v5
	v_add_f32_e32 v6, 1.0, v6
	v_add_f32_e32 v7, 1.0, v7
	v_rcp_f32_e32 v148, v148
	v_rcp_f32_e32 v149, v149
	v_rcp_f32_e32 v150, v150
	v_rcp_f32_e32 v151, v151
	v_rcp_f32_e32 v4, v4
	v_rcp_f32_e32 v5, v5
	v_rcp_f32_e32 v6, v6
	v_rcp_f32_e32 v7, v7
	v_mul_f32_e32 v240, v148, v240
	v_mul_f32_e32 v241, v149, v241
	v_mul_f32_e32 v242, v150, v242
	v_mul_f32_e32 v243, v151, v243
	v_mul_f32_e32 v244, v4, v244
	v_mul_f32_e32 v245, v5, v245
	v_mul_f32_e32 v246, v6, v246
	v_mul_f32_e32 v247, v7, v247
	v_mul_f32_e32 v148, 0xbfb8aa3b, v248
	v_mul_f32_e32 v149, 0xbfb8aa3b, v249
	v_mul_f32_e32 v150, 0xbfb8aa3b, v250
	v_mul_f32_e32 v151, 0xbfb8aa3b, v251
	v_mul_f32_e32 v4, 0xbfb8aa3b, v252
	v_mul_f32_e32 v5, 0xbfb8aa3b, v253
	v_mul_f32_e32 v6, 0xbfb8aa3b, v254
	v_mul_f32_e32 v7, 0xbfb8aa3b, v255
	v_exp_f32_e32 v148, v148
	v_exp_f32_e32 v149, v149
	v_exp_f32_e32 v150, v150
	v_exp_f32_e32 v151, v151
	v_exp_f32_e32 v4, v4
	v_exp_f32_e32 v5, v5
	v_exp_f32_e32 v6, v6
	v_exp_f32_e32 v7, v7
	v_add_f32_e32 v148, 1.0, v148
	v_add_f32_e32 v149, 1.0, v149
	v_add_f32_e32 v150, 1.0, v150
	v_add_f32_e32 v151, 1.0, v151
	v_add_f32_e32 v4, 1.0, v4
	v_add_f32_e32 v5, 1.0, v5
	v_add_f32_e32 v6, 1.0, v6
	v_add_f32_e32 v7, 1.0, v7
	v_rcp_f32_e32 v148, v148
	v_rcp_f32_e32 v149, v149
	v_rcp_f32_e32 v150, v150
	v_rcp_f32_e32 v151, v151
	v_rcp_f32_e32 v4, v4
	v_rcp_f32_e32 v5, v5
	v_rcp_f32_e32 v6, v6
	v_rcp_f32_e32 v7, v7
	v_mul_f32_e32 v248, v148, v248
	v_mul_f32_e32 v249, v149, v249
	v_mul_f32_e32 v250, v150, v250
	v_mul_f32_e32 v251, v151, v251
	v_mul_f32_e32 v252, v4, v252
	v_mul_f32_e32 v253, v5, v253
	v_mul_f32_e32 v254, v6, v254
	v_mul_f32_e32 v255, v7, v255
	v_mul_f32_e32 v214, v144, v214
	v_mul_f32_e32 v215, v144, v215
	v_mul_f32_e32 v216, v144, v216
	v_mul_f32_e32 v217, v144, v217
	v_mul_f32_e32 v218, v144, v218
	v_mul_f32_e32 v219, v144, v219
	v_mul_f32_e32 v220, v144, v220
	v_mul_f32_e32 v221, v144, v221
	v_mul_f32_e32 v222, v145, v222
	v_mul_f32_e32 v223, v145, v223
	v_mul_f32_e32 v224, v145, v224
	v_mul_f32_e32 v225, v145, v225
	v_mul_f32_e32 v226, v145, v226
	v_mul_f32_e32 v227, v145, v227
	v_mul_f32_e32 v228, v145, v228
	v_mul_f32_e32 v229, v145, v229
	v_mul_f32_e32 v214, v16, v214
	v_mul_f32_e32 v215, v17, v215
	v_mul_f32_e32 v216, v18, v216
	v_mul_f32_e32 v217, v19, v217
	v_mul_f32_e32 v218, v20, v218
	v_mul_f32_e32 v219, v21, v219
	v_mul_f32_e32 v220, v22, v220
	v_mul_f32_e32 v221, v23, v221
	v_mul_f32_e32 v222, v24, v222
	v_mul_f32_e32 v223, v25, v223
	v_mul_f32_e32 v224, v26, v224
	v_mul_f32_e32 v225, v27, v225
	v_mul_f32_e32 v226, v28, v226
	v_mul_f32_e32 v227, v29, v227
	v_mul_f32_e32 v228, v30, v228
	v_mul_f32_e32 v229, v31, v229
	v_mul_f32_e32 v214, v240, v214
	v_mul_f32_e32 v215, v241, v215
	v_mul_f32_e32 v216, v242, v216
	v_mul_f32_e32 v217, v243, v217
	v_mul_f32_e32 v218, v244, v218
	v_mul_f32_e32 v219, v245, v219
	v_mul_f32_e32 v220, v246, v220
	v_mul_f32_e32 v221, v247, v221
	v_mul_f32_e32 v222, v248, v222
	v_mul_f32_e32 v223, v249, v223
	v_mul_f32_e32 v224, v250, v224
	v_mul_f32_e32 v225, v251, v225
	v_mul_f32_e32 v226, v252, v226
	v_mul_f32_e32 v227, v253, v227
	v_mul_f32_e32 v228, v254, v228
	v_mul_f32_e32 v229, v255, v229
	v_cvt_pk_bf16_f32 v144, v214, v215
	v_cvt_pk_bf16_f32 v145, v216, v217
	v_cvt_pk_bf16_f32 v146, v218, v219
	v_cvt_pk_bf16_f32 v147, v220, v221
	v_cvt_pk_bf16_f32 v148, v222, v223
	v_cvt_pk_bf16_f32 v149, v224, v225
	v_cvt_pk_bf16_f32 v150, v226, v227
	v_cvt_pk_bf16_f32 v151, v228, v229
	s_mul_i32 s9, s46, 7
	s_add_i32 s9, s9, s8
	s_lshl_b32 s3, s9, 11
	s_add_u32 s24, s16, s3
	s_addc_u32 s25, s17, 0
	global_store_dwordx4 v2, v[144:147], s[24:25]
	global_store_dwordx4 v2, v[148:151], s[24:25] offset:1024
	s_cmpk_lt_u32 s8, 0x400
	s_cbranch_scc0 .Lg4_done
; DI unsigned pk_bf16(float a, float b) { f32x2 v = {a, b}; bf2_t r = __builtin_convertvector(v, bf2_t); return __builtin_bit_cast(unsigned, r); }
; DI float bflo(unsigned u) { return __uint_as_float(u << 16); }
; DI float bfhi(unsigned u) { return __uint_as_float(u & 0xffff0000u); }
; DI float silu_f(float x) { return x * __builtin_amdgcn_rcpf(1.f + __expf(-x)); }
; DI void phase_gdn_gate(const Params& p) {
;     ...
;     for (int tok = gw; tok < T_TOK; tok += nw) {
;         const u32x4 a0 = *(const u32x4*)(oraw + (size_t)tok * 1024 + 16 * lane), a1 = *(const u32x4*)(oraw + (size_t)tok * 1024 + 16 * lane + 8);
;         const u32x4 z0 = *(const u32x4*)(P0 + (size_t)tok * LDP0 + 3072 + 16 * lane), z1 = *(const u32x4*)(P0 + (size_t)tok * LDP0 + 3072 + 16 * lane + 8);
;         float o[16], z[16];
;         const unsigned au[8] = {a0.x, a0.y, a0.z, a0.w, a1.x, a1.y, a1.z, a1.w}, zu[8] = {z0.x, z0.y, z0.z, z0.w, z1.x, z1.y, z1.z, z1.w};
;         float ss = 0.f;
; #pragma unroll
;         for (int i = 0; i < 8; ++i) { o[2 * i] = bflo(au[i]); o[2 * i + 1] = bfhi(au[i]); z[2 * i] = bflo(zu[i]); z[2 * i + 1] = bfhi(zu[i]); ss += o[2 * i] * o[2 * i] + o[2 * i + 1] * o[2 * i + 1]; }
;         ss += __shfl_xor(ss, 1); ss += __shfl_xor(ss, 2); ss += __shfl_xor(ss, 4);
;         const float rstd = rsqrtf(ss * (1.f / 128.f) + 1e-6f);
;         const int d0 = (16 * lane) & 127;
;         unsigned r[8];
; #pragma unroll
;         for (int i = 0; i < 8; ++i) { const float v0 = o[2 * i] * rstd * p.onorm_a[d0 + 2 * i] * silu_f(z[2 * i]), v1 = o[2 * i + 1] * rstd * p.onorm_a[d0 + 2 * i + 1] * silu_f(z[2 * i + 1]); r[i] = pk_bf16(v0, v1); }
;         *(u32x4*)(og + (size_t)tok * 1024 + 16 * lane) = (u32x4){r[0], r[1], r[2], r[3]};
;         *(u32x4*)(og + (size_t)tok * 1024 + 16 * lane + 8) = (u32x4){r[4], r[5], r[6], r[7]};
	s_waitcnt vmcnt(16)
	v_lshlrev_b32_e32 v214, 16, v198
	v_and_b32_e32 v215, 0xffff0000, v198
	v_lshlrev_b32_e32 v216, 16, v199
	v_and_b32_e32 v217, 0xffff0000, v199
	v_lshlrev_b32_e32 v218, 16, v200
	v_and_b32_e32 v219, 0xffff0000, v200
	v_lshlrev_b32_e32 v220, 16, v201
	v_and_b32_e32 v221, 0xffff0000, v201
	v_lshlrev_b32_e32 v222, 16, v202
	v_and_b32_e32 v223, 0xffff0000, v202
	v_lshlrev_b32_e32 v224, 16, v203
	v_and_b32_e32 v225, 0xffff0000, v203
	v_lshlrev_b32_e32 v226, 16, v204
	v_and_b32_e32 v227, 0xffff0000, v204
	v_lshlrev_b32_e32 v228, 16, v205
	v_and_b32_e32 v229, 0xffff0000, v205
	v_mul_f32_e32 v144, v214, v214
	v_fmac_f32_e32 v144, v215, v215
	v_fmac_f32_e32 v144, v216, v216
	v_fmac_f32_e32 v144, v217, v217
	v_fmac_f32_e32 v144, v218, v218
	v_fmac_f32_e32 v144, v219, v219
	v_fmac_f32_e32 v144, v220, v220
	v_fmac_f32_e32 v144, v221, v221
	v_mul_f32_e32 v145, v222, v222
	v_fmac_f32_e32 v145, v223, v223
	v_fmac_f32_e32 v145, v224, v224
	v_fmac_f32_e32 v145, v225, v225
	v_fmac_f32_e32 v145, v226, v226
	v_fmac_f32_e32 v145, v227, v227
	v_fmac_f32_e32 v145, v228, v228
	v_fmac_f32_e32 v145, v229, v229
	v_lshlrev_b32_e32 v240, 16, v206
	v_and_b32_e32 v241, 0xffff0000, v206
	v_lshlrev_b32_e32 v242, 16, v207
	v_and_b32_e32 v243, 0xffff0000, v207
	v_lshlrev_b32_e32 v244, 16, v208
	v_and_b32_e32 v245, 0xffff0000, v208
	v_lshlrev_b32_e32 v246, 16, v209
	v_and_b32_e32 v247, 0xffff0000, v209
	v_lshlrev_b32_e32 v248, 16, v210
	v_and_b32_e32 v249, 0xffff0000, v210
	v_lshlrev_b32_e32 v250, 16, v211
	v_and_b32_e32 v251, 0xffff0000, v211
	v_lshlrev_b32_e32 v252, 16, v212
	v_and_b32_e32 v253, 0xffff0000, v212
	v_lshlrev_b32_e32 v254, 16, v213
	v_and_b32_e32 v255, 0xffff0000, v213
	s_nop 1
	v_add_f32_dpp v144, v144, v144 quad_perm:[1,0,3,2] row_mask:0xf bank_mask:0xf
	v_add_f32_dpp v145, v145, v145 quad_perm:[1,0,3,2] row_mask:0xf bank_mask:0xf
	s_nop 1
	v_add_f32_dpp v144, v144, v144 quad_perm:[2,3,0,1] row_mask:0xf bank_mask:0xf
	v_add_f32_dpp v145, v145, v145 quad_perm:[2,3,0,1] row_mask:0xf bank_mask:0xf
	s_nop 1
	v_add_f32_dpp v144, v144, v144 row_ror:4 row_mask:0xf bank_mask:0xf
	v_add_f32_dpp v145, v145, v145 row_ror:4 row_mask:0xf bank_mask:0xf
	s_nop 1
	v_add_f32_dpp v144, v144, v144 row_ror:8 row_mask:0xf bank_mask:0xf
	v_add_f32_dpp v145, v145, v145 row_ror:8 row_mask:0xf bank_mask:0xf
	v_fmamk_f32 v144, v144, 0x3c000000, v15
	v_fmamk_f32 v145, v145, 0x3c000000, v15
	v_rsq_f32_e32 v144, v144
	v_rsq_f32_e32 v145, v145
	v_mul_f32_e32 v148, 0xbfb8aa3b, v240
	v_mul_f32_e32 v149, 0xbfb8aa3b, v241
	v_mul_f32_e32 v150, 0xbfb8aa3b, v242
	v_mul_f32_e32 v151, 0xbfb8aa3b, v243
	v_mul_f32_e32 v4, 0xbfb8aa3b, v244
	v_mul_f32_e32 v5, 0xbfb8aa3b, v245
	v_mul_f32_e32 v6, 0xbfb8aa3b, v246
	v_mul_f32_e32 v7, 0xbfb8aa3b, v247
	v_exp_f32_e32 v148, v148
	v_exp_f32_e32 v149, v149
	v_exp_f32_e32 v150, v150
	v_exp_f32_e32 v151, v151
	v_exp_f32_e32 v4, v4
	v_exp_f32_e32 v5, v5
	v_exp_f32_e32 v6, v6
	v_exp_f32_e32 v7, v7
	v_add_f32_e32 v148, 1.0, v148
	v_add_f32_e32 v149, 1.0, v149
	v_add_f32_e32 v150, 1.0, v150
	v_add_f32_e32 v151, 1.0, v151
	v_add_f32_e32 v4, 1.0, v4
	v_add_f32_e32 v5, 1.0, v5
	v_add_f32_e32 v6, 1.0, v6
	v_add_f32_e32 v7, 1.0, v7
	v_rcp_f32_e32 v148, v148
	v_rcp_f32_e32 v149, v149
	v_rcp_f32_e32 v150, v150
	v_rcp_f32_e32 v151, v151
	v_rcp_f32_e32 v4, v4
	v_rcp_f32_e32 v5, v5
	v_rcp_f32_e32 v6, v6
	v_rcp_f32_e32 v7, v7
	v_mul_f32_e32 v240, v148, v240
	v_mul_f32_e32 v241, v149, v241
	v_mul_f32_e32 v242, v150, v242
	v_mul_f32_e32 v243, v151, v243
	v_mul_f32_e32 v244, v4, v244
	v_mul_f32_e32 v245, v5, v245
	v_mul_f32_e32 v246, v6, v246
	v_mul_f32_e32 v247, v7, v247
	v_mul_f32_e32 v148, 0xbfb8aa3b, v248
	v_mul_f32_e32 v149, 0xbfb8aa3b, v249
	v_mul_f32_e32 v150, 0xbfb8aa3b, v250
	v_mul_f32_e32 v151, 0xbfb8aa3b, v251
	v_mul_f32_e32 v4, 0xbfb8aa3b, v252
	v_mul_f32_e32 v5, 0xbfb8aa3b, v253
	v_mul_f32_e32 v6, 0xbfb8aa3b, v254
	v_mul_f32_e32 v7, 0xbfb8aa3b, v255
	v_exp_f32_e32 v148, v148
	v_exp_f32_e32 v149, v149
	v_exp_f32_e32 v150, v150
	v_exp_f32_e32 v151, v151
	v_exp_f32_e32 v4, v4
	v_exp_f32_e32 v5, v5
	v_exp_f32_e32 v6, v6
	v_exp_f32_e32 v7, v7
	v_add_f32_e32 v148, 1.0, v148
	v_add_f32_e32 v149, 1.0, v149
	v_add_f32_e32 v150, 1.0, v150
	v_add_f32_e32 v151, 1.0, v151
	v_add_f32_e32 v4, 1.0, v4
	v_add_f32_e32 v5, 1.0, v5
	v_add_f32_e32 v6, 1.0, v6
	v_add_f32_e32 v7, 1.0, v7
	v_rcp_f32_e32 v148, v148
	v_rcp_f32_e32 v149, v149
	v_rcp_f32_e32 v150, v150
	v_rcp_f32_e32 v151, v151
	v_rcp_f32_e32 v4, v4
	v_rcp_f32_e32 v5, v5
	v_rcp_f32_e32 v6, v6
	v_rcp_f32_e32 v7, v7
	v_mul_f32_e32 v248, v148, v248
	v_mul_f32_e32 v249, v149, v249
	v_mul_f32_e32 v250, v150, v250
	v_mul_f32_e32 v251, v151, v251
	v_mul_f32_e32 v252, v4, v252
	v_mul_f32_e32 v253, v5, v253
	v_mul_f32_e32 v254, v6, v254
	v_mul_f32_e32 v255, v7, v255
	v_mul_f32_e32 v214, v144, v214
	v_mul_f32_e32 v215, v144, v215
	v_mul_f32_e32 v216, v144, v216
	v_mul_f32_e32 v217, v144, v217
	v_mul_f32_e32 v218, v144, v218
	v_mul_f32_e32 v219, v144, v219
	v_mul_f32_e32 v220, v144, v220
	v_mul_f32_e32 v221, v144, v221
	v_mul_f32_e32 v222, v145, v222
	v_mul_f32_e32 v223, v145, v223
	v_mul_f32_e32 v224, v145, v224
	v_mul_f32_e32 v225, v145, v225
	v_mul_f32_e32 v226, v145, v226
	v_mul_f32_e32 v227, v145, v227
	v_mul_f32_e32 v228, v145, v228
	v_mul_f32_e32 v229, v145, v229
	v_mul_f32_e32 v214, v16, v214
	v_mul_f32_e32 v215, v17, v215
	v_mul_f32_e32 v216, v18, v216
	v_mul_f32_e32 v217, v19, v217
	v_mul_f32_e32 v218, v20, v218
	v_mul_f32_e32 v219, v21, v219
	v_mul_f32_e32 v220, v22, v220
	v_mul_f32_e32 v221, v23, v221
	v_mul_f32_e32 v222, v24, v222
	v_mul_f32_e32 v223, v25, v223
	v_mul_f32_e32 v224, v26, v224
	v_mul_f32_e32 v225, v27, v225
	v_mul_f32_e32 v226, v28, v226
	v_mul_f32_e32 v227, v29, v227
	v_mul_f32_e32 v228, v30, v228
	v_mul_f32_e32 v229, v31, v229
	v_mul_f32_e32 v214, v240, v214
	v_mul_f32_e32 v215, v241, v215
	v_mul_f32_e32 v216, v242, v216
	v_mul_f32_e32 v217, v243, v217
	v_mul_f32_e32 v218, v244, v218
	v_mul_f32_e32 v219, v245, v219
	v_mul_f32_e32 v220, v246, v220
	v_mul_f32_e32 v221, v247, v221
	v_mul_f32_e32 v222, v248, v222
	v_mul_f32_e32 v223, v249, v223
	v_mul_f32_e32 v224, v250, v224
	v_mul_f32_e32 v225, v251, v225
	v_mul_f32_e32 v226, v252, v226
	v_mul_f32_e32 v227, v253, v227
	v_mul_f32_e32 v228, v254, v228
	v_mul_f32_e32 v229, v255, v229
	v_cvt_pk_bf16_f32 v144, v214, v215
	v_cvt_pk_bf16_f32 v145, v216, v217
	v_cvt_pk_bf16_f32 v146, v218, v219
	v_cvt_pk_bf16_f32 v147, v220, v221
	v_cvt_pk_bf16_f32 v148, v222, v223
	v_cvt_pk_bf16_f32 v149, v224, v225
	v_cvt_pk_bf16_f32 v150, v226, v227
	v_cvt_pk_bf16_f32 v151, v228, v229
	s_mul_i32 s9, s46, 8
	s_add_i32 s9, s9, s8
	s_lshl_b32 s3, s9, 11
	s_add_u32 s24, s16, s3
	s_addc_u32 s25, s17, 0
	global_store_dwordx4 v2, v[144:147], s[24:25]
	global_store_dwordx4 v2, v[148:151], s[24:25] offset:1024

; DI float bflo(unsigned u) { return __uint_as_float(u << 16); }
; DI float bfhi(unsigned u) { return __uint_as_float(u & 0xffff0000u); }
; DI void phase_ret_gate(const Params& p) {
;     const int lane = threadIdx.x & 63, gw = blockIdx.x * 8 + (threadIdx.x >> 6), nw = gridDim.x * 8;
;     const bf16_t* oraw = (const bf16_t*)(p.ws + WS_ORAW); const bf16_t* P1 = (const bf16_t*)(p.ws + WS_P1); bf16_t* og = (bf16_t*)(p.ws + WS_OG);
;     for (int tok = gw; tok < T_TOK; tok += nw) {
;         float o[32]; float ss = 0.f;
; #pragma unroll
;         for (int q = 0; q < 4; ++q) { const u32x4 a = *(const u32x4*)(oraw + (size_t)tok * 2048 + 32 * lane + 8 * q); const unsigned au[4] = {a.x, a.y, a.z, a.w};
; #pragma unroll
;             for (int i = 0; i < 4; ++i) { o[8 * q + 2 * i] = bflo(au[i]); o[8 * q + 2 * i + 1] = bfhi(au[i]); ss += o[8 * q + 2 * i] * o[8 * q + 2 * i] + o[8 * q + 2 * i + 1] * o[8 * q + 2 * i + 1]; } }
;         ss = row16_sum(ss);
;         const float rstd = rsqrtf(ss * (1.f / 512.f) + 1e-6f);
;         const float* wn = p.onorm_b + 32 * lane;
; #pragma unroll
;         for (int q = 0; q < 4; ++q) { const u32x4 g = *(const u32x4*)(P1 + (size_t)tok * LDP1 + 4096 + 32 * lane + 8 * q); const unsigned gu[4] = {g.x, g.y, g.z, g.w}; unsigned r[4];
.LBB0_1446:
	s_cmp_lt_i32 s80, 11
	s_cselect_b64 s[4:5], -1, 0
	s_and_b64 s[0:1], s[4:5], s[0:1]
	s_and_b64 s[0:1], s[44:45], s[0:1]
	s_and_saveexec_b64 s[6:7], s[0:1]
	s_cbranch_execz .LBB0_1449
	v_readlane_b32 s14, v238, 12
	v_readlane_b32 s15, v238, 13
	v_lshlrev_b32_e32 v2, 4, v196
	v_lshlrev_b32_e32 v3, 5, v196
	v_add_u32_e32 v6, 0x1000, v3
	s_add_u32 s10, s78, 0x3c80000
	s_addc_u32 s11, s79, 0
	s_add_u32 s12, s78, 0x1d482000
	s_addc_u32 s13, s79, 0
	s_add_u32 s16, s78, 0x8080000
	s_addc_u32 s17, s79, 0
	global_load_dwordx4 v[16:19], v3, s[14:15] nt
	global_load_dwordx4 v[20:23], v3, s[14:15] offset:16 nt
	global_load_dwordx4 v[24:27], v3, s[14:15] offset:2048 nt
	global_load_dwordx4 v[28:31], v3, s[14:15] offset:2064 nt
	global_load_dwordx4 v[32:35], v6, s[14:15] nt
	global_load_dwordx4 v[36:39], v6, s[14:15] offset:16 nt
	global_load_dwordx4 v[40:43], v6, s[14:15] offset:2048 nt
	global_load_dwordx4 v[44:47], v6, s[14:15] offset:2064 nt
	v_readfirstlane_b32 s8, v162
	s_mov_b32 s23, 0
	v_mov_b32_e32 v15, 0x358637bd
	s_lshl_b32 s9, s8, 12
	v_add_u32_e32 v4, s9, v2
	s_mul_i32 s9, s8, 0x3000
	v_add_u32_e32 v5, s9, v2
	global_load_dwordx4 v[48:51], v4, s[10:11] nt
	global_load_dwordx4 v[52:55], v4, s[10:11] offset:1024 nt
	global_load_dwordx4 v[56:59], v4, s[10:11] offset:2048 nt
	global_load_dwordx4 v[60:63], v4, s[10:11] offset:3072 nt
	global_load_dwordx4 v[64:67], v5, s[12:13] nt
	global_load_dwordx4 v[68:71], v5, s[12:13] offset:1024 nt
	global_load_dwordx4 v[72:75], v5, s[12:13] offset:2048 nt
	global_load_dwordx4 v[76:79], v5, s[12:13] offset:3072 nt
.Lg10_a:
	s_add_u32 s22, s8, s46
	s_cmp_lt_u32 s22, 0x4400
	s_cbranch_scc0 .Lg10_a_nonext
	s_lshl_b32 s9, s22, 12
	v_add_u32_e32 v4, s9, v2
	s_mul_i32 s9, s22, 0x3000
	v_add_u32_e32 v5, s9, v2
	global_load_dwordx4 v[80:83], v4, s[10:11] nt
	global_load_dwordx4 v[84:87], v4, s[10:11] offset:1024 nt
	global_load_dwordx4 v[88:91], v4, s[10:11] offset:2048 nt
	global_load_dwordx4 v[92:95], v4, s[10:11] offset:3072 nt
	global_load_dwordx4 v[96:99], v5, s[12:13] nt
	global_load_dwordx4 v[100:103], v5, s[12:13] offset:1024 nt
	global_load_dwordx4 v[104:107], v5, s[12:13] offset:2048 nt
	global_load_dwordx4 v[108:111], v5, s[12:13] offset:3072 nt
	s_cmp_eq_u32 s23, 0
	s_cbranch_scc1 .Lg10_a_w8
	s_waitcnt vmcnt(12)
	s_branch .Lg10_a_have

; DI float bflo(unsigned u) { return __uint_as_float(u << 16); }
; DI float bfhi(unsigned u) { return __uint_as_float(u & 0xffff0000u); }
; DI void phase_ret_gate(const Params& p) {
;     ...
;     for (int tok = gw; tok < T_TOK; tok += nw) {
;         float o[32]; float ss = 0.f;
; #pragma unroll
;         for (int q = 0; q < 4; ++q) { const u32x4 a = *(const u32x4*)(oraw + (size_t)tok * 2048 + 32 * lane + 8 * q); const unsigned au[4] = {a.x, a.y, a.z, a.w};
; #pragma unroll
;             for (int i = 0; i < 4; ++i) { o[8 * q + 2 * i] = bflo(au[i]); o[8 * q + 2 * i + 1] = bfhi(au[i]); ss += o[8 * q + 2 * i] * o[8 * q + 2 * i] + o[8 * q + 2 * i + 1] * o[8 * q + 2 * i + 1]; } }
;         ss = row16_sum(ss);
;         const float rstd = rsqrtf(ss * (1.f / 512.f) + 1e-6f);
;         const float* wn = p.onorm_b + 32 * lane;
; #pragma unroll
;         for (int q = 0; q < 4; ++q) { const u32x4 g = *(const u32x4*)(P1 + (size_t)tok * LDP1 + 4096 + 32 * lane + 8 * q); const unsigned gu[4] = {g.x, g.y, g.z, g.w}; unsigned r[4];
.Lg10_b:
	s_add_u32 s22, s8, s46
	s_cmp_lt_u32 s22, 0x4400
	s_cbranch_scc0 .Lg10_b_nonext
	s_lshl_b32 s9, s22, 12
	v_add_u32_e32 v4, s9, v2
	s_mul_i32 s9, s22, 0x3000
	v_add_u32_e32 v5, s9, v2
	global_load_dwordx4 v[48:51], v4, s[10:11] nt
	global_load_dwordx4 v[52:55], v4, s[10:11] offset:1024 nt
	global_load_dwordx4 v[56:59], v4, s[10:11] offset:2048 nt
	global_load_dwordx4 v[60:63], v4, s[10:11] offset:3072 nt
	global_load_dwordx4 v[64:67], v5, s[12:13] nt
	global_load_dwordx4 v[68:71], v5, s[12:13] offset:1024 nt
	global_load_dwordx4 v[72:75], v5, s[12:13] offset:2048 nt
	global_load_dwordx4 v[76:79], v5, s[12:13] offset:3072 nt
	s_cmp_eq_u32 s23, 0
	s_cbranch_scc1 .Lg10_b_w8
	s_waitcnt vmcnt(12)
	s_branch .Lg10_b_have
